# K-loop bodies regenerated: second-half fragments prefetched into a second register set during first-half MFMA gaps, counted lgkmcnt
# baseline (speedup 1.0000x reference)
; #define MFMA16(a, b, c) __builtin_amdgcn_mfma_f32_16x16x32_bf16((a), (b), (c), 0, 0, 0)
;     ...
;   for (int kt = 0; kt < nk; ++kt) {
;     const int buf = kt & 1;
;     const char* cA = smem + buf * STAGE + (wm * 32 * MI + r16) * 128;
;     const char* cB = smem + buf * STAGE + 32768 + (wn * 64 + r16) * 128;
; #pragma unroll
;     for (int k2 = 0; k2 < 2; ++k2) {
;       if (k2 == 1 && kt + 1 < nk) STAGE_TILE(buf ^ 1, (kt + 1) * 64)
;       const int po = ((4 * k2 + q4) ^ swz) * 16;
;       bf16x8 bf[4];
; #pragma unroll
;       for (int nt = 0; nt < 4; ++nt) bf[nt] = *(const bf16x8*)(cB + nt * 16 * 128 + po);
;       bf16x8 afc = *(const bf16x8*)(cA + po);
; #pragma unroll
;       for (int a = 0; a < MT; ++a) {
;         bf16x8 afn = afc;
;         if (a + 1 < MT) afn = *(const bf16x8*)(cA + (a + 1) * 16 * 128 + po);
;         __builtin_amdgcn_sched_barrier(0);
; #pragma unroll
;         for (int nt = 0; nt < 4; ++nt) acc[a][nt] = MFMA16(bf[nt], afc, acc[a][nt]);
;         __builtin_amdgcn_sched_barrier(0);
;         afc = afn;
;       }
;     }
;     asm volatile("s_waitcnt vmcnt(0)" ::: "memory");
;     __syncthreads();
;   }
.LBB0_48:
	s_and_b32 s42, s41, 0x10000
	s_add_i32 s43, s42, 0
	s_xor_b32 s42, s42, 0x10000
	v_add_u32_e32 v174, s43, v147
	v_add_u32_e32 v162, v174, v146
	v_add_u32_e32 v149, s43, v148
	ds_read_b128 v[150:153], v162 offset:32768
	ds_read_b128 v[154:157], v162 offset:34816
	ds_read_b128 v[158:161], v162 offset:36864
	ds_read_b128 v[162:165], v162 offset:38912
	v_add_u32_e32 v175, v149, v146
	ds_read_b128 v[166:169], v175
	ds_read_b128 v[170:173], v175 offset:2048
	s_waitcnt lgkmcnt(1)
	v_mfma_f32_16x16x32_bf16 v[126:129], v[150:153], v[166:169], v[126:129]
	v_readfirstlane_b32 s43, v145
	v_mfma_f32_16x16x32_bf16 v[122:125], v[154:157], v[166:169], v[122:125]
	s_nop 0
	v_mfma_f32_16x16x32_bf16 v[118:121], v[158:161], v[166:169], v[118:121]
	s_add_u32 s43, s43, s42
	v_mfma_f32_16x16x32_bf16 v[114:117], v[162:165], v[166:169], v[114:117]
	ds_read_b128 v[166:169], v175 offset:4096
	s_add_u32 m0, s43, 0x0
	s_waitcnt lgkmcnt(1)
	v_mfma_f32_16x16x32_bf16 v[110:113], v[150:153], v[170:173], v[110:113]
	global_load_lds_dwordx4 v176, s[100:101]
	v_mfma_f32_16x16x32_bf16 v[106:109], v[154:157], v[170:173], v[106:109]
	s_add_u32 m0, s43, 0x2000
	v_mfma_f32_16x16x32_bf16 v[102:105], v[158:161], v[170:173], v[102:105]
	global_load_lds_dwordx4 v177, s[100:101]
	v_mfma_f32_16x16x32_bf16 v[98:101], v[162:165], v[170:173], v[98:101]
	ds_read_b128 v[170:173], v175 offset:6144
	s_add_u32 m0, s43, 0x4000
	s_waitcnt lgkmcnt(1)
	v_mfma_f32_16x16x32_bf16 v[94:97], v[150:153], v[166:169], v[94:97]
	global_load_lds_dwordx4 v178, s[100:101]
	v_mfma_f32_16x16x32_bf16 v[90:93], v[154:157], v[166:169], v[90:93]
	s_add_u32 m0, s43, 0x6000
	v_mfma_f32_16x16x32_bf16 v[86:89], v[158:161], v[166:169], v[86:89]
	global_load_lds_dwordx4 v179, s[100:101]
	v_mfma_f32_16x16x32_bf16 v[82:85], v[162:165], v[166:169], v[82:85]
	ds_read_b128 v[166:169], v175 offset:8192
	s_add_u32 m0, s43, 0x8000
	s_waitcnt lgkmcnt(1)
	v_mfma_f32_16x16x32_bf16 v[78:81], v[150:153], v[170:173], v[78:81]
	global_load_lds_dwordx4 v180, s[100:101]
	v_mfma_f32_16x16x32_bf16 v[74:77], v[154:157], v[170:173], v[74:77]
	s_add_u32 m0, s43, 0xa000
	v_mfma_f32_16x16x32_bf16 v[70:73], v[158:161], v[170:173], v[70:73]
	global_load_lds_dwordx4 v181, s[100:101]
	v_mfma_f32_16x16x32_bf16 v[66:69], v[162:165], v[170:173], v[66:69]
	ds_read_b128 v[170:173], v175 offset:10240
	s_add_u32 m0, s43, 0xc000
	s_waitcnt lgkmcnt(1)
	v_mfma_f32_16x16x32_bf16 v[62:65], v[150:153], v[166:169], v[62:65]
	global_load_lds_dwordx4 v182, s[100:101]
	v_mfma_f32_16x16x32_bf16 v[58:61], v[154:157], v[166:169], v[58:61]
	s_add_u32 m0, s43, 0xe000
	v_mfma_f32_16x16x32_bf16 v[54:57], v[158:161], v[166:169], v[54:57]
	global_load_lds_dwordx4 v183, s[100:101]
	v_mfma_f32_16x16x32_bf16 v[50:53], v[162:165], v[166:169], v[50:53]
	ds_read_b128 v[166:169], v175 offset:12288
	v_add_u32_e32 v203, v174, v144
	s_waitcnt lgkmcnt(1)
	v_mfma_f32_16x16x32_bf16 v[46:49], v[150:153], v[170:173], v[46:49]
	v_add_u32_e32 v192, v149, v144
	v_mfma_f32_16x16x32_bf16 v[42:45], v[154:157], v[170:173], v[42:45]
	ds_read_b128 v[204:207], v203 offset:32768
	v_mfma_f32_16x16x32_bf16 v[38:41], v[158:161], v[170:173], v[38:41]
	ds_read_b128 v[208:211], v203 offset:34816
	v_mfma_f32_16x16x32_bf16 v[34:37], v[162:165], v[170:173], v[34:37]
	ds_read_b128 v[170:173], v175 offset:14336
	ds_read_b128 v[212:215], v203 offset:36864
	s_waitcnt lgkmcnt(4)
	v_mfma_f32_16x16x32_bf16 v[30:33], v[150:153], v[166:169], v[30:33]
	ds_read_b128 v[216:219], v203 offset:38912
	v_mfma_f32_16x16x32_bf16 v[26:29], v[154:157], v[166:169], v[26:29]
	ds_read_b128 v[220:223], v192
	v_mfma_f32_16x16x32_bf16 v[22:25], v[158:161], v[166:169], v[22:25]
	ds_read_b128 v[198:201], v192 offset:2048
	v_mfma_f32_16x16x32_bf16 v[18:21], v[162:165], v[166:169], v[18:21]
	s_waitcnt lgkmcnt(4)
	v_mfma_f32_16x16x32_bf16 v[14:17], v[150:153], v[170:173], v[14:17]
	v_mfma_f32_16x16x32_bf16 v[10:13], v[154:157], v[170:173], v[10:13]
	v_mfma_f32_16x16x32_bf16 v[6:9], v[158:161], v[170:173], v[6:9]
	v_mfma_f32_16x16x32_bf16 v[2:5], v[162:165], v[170:173], v[2:5]
	s_waitcnt lgkmcnt(1)
	v_mfma_f32_16x16x32_bf16 v[126:129], v[204:207], v[220:223], v[126:129]
	s_add_u32 s100, s100, 0x80
	v_mfma_f32_16x16x32_bf16 v[122:125], v[208:211], v[220:223], v[122:125]
	s_addc_u32 s101, s101, 0
	v_mfma_f32_16x16x32_bf16 v[118:121], v[212:215], v[220:223], v[118:121]
	s_add_u32 s16, s16, 0x80
	v_mfma_f32_16x16x32_bf16 v[114:117], v[216:219], v[220:223], v[114:117]
	ds_read_b128 v[220:223], v192 offset:4096
	s_waitcnt lgkmcnt(1)
	v_mfma_f32_16x16x32_bf16 v[110:113], v[204:207], v[198:201], v[110:113]
	s_addc_u32 s17, s17, 0
	v_mfma_f32_16x16x32_bf16 v[106:109], v[208:211], v[198:201], v[106:109]
	s_add_i32 s41, s41, 0x10000
	v_mfma_f32_16x16x32_bf16 v[102:105], v[212:215], v[198:201], v[102:105]
	v_mfma_f32_16x16x32_bf16 v[98:101], v[216:219], v[198:201], v[98:101]
	ds_read_b128 v[198:201], v192 offset:6144
	s_waitcnt lgkmcnt(1)
	v_mfma_f32_16x16x32_bf16 v[94:97], v[204:207], v[220:223], v[94:97]
	v_mfma_f32_16x16x32_bf16 v[90:93], v[208:211], v[220:223], v[90:93]
	v_mfma_f32_16x16x32_bf16 v[86:89], v[212:215], v[220:223], v[86:89]
	v_mfma_f32_16x16x32_bf16 v[82:85], v[216:219], v[220:223], v[82:85]
	ds_read_b128 v[220:223], v192 offset:8192
	s_waitcnt lgkmcnt(1)
	v_mfma_f32_16x16x32_bf16 v[78:81], v[204:207], v[198:201], v[78:81]
	v_mfma_f32_16x16x32_bf16 v[74:77], v[208:211], v[198:201], v[74:77]
	v_mfma_f32_16x16x32_bf16 v[70:73], v[212:215], v[198:201], v[70:73]
	v_mfma_f32_16x16x32_bf16 v[66:69], v[216:219], v[198:201], v[66:69]
	ds_read_b128 v[198:201], v192 offset:10240
	s_waitcnt lgkmcnt(1)
	v_mfma_f32_16x16x32_bf16 v[62:65], v[204:207], v[220:223], v[62:65]
	v_mfma_f32_16x16x32_bf16 v[58:61], v[208:211], v[220:223], v[58:61]
	v_mfma_f32_16x16x32_bf16 v[54:57], v[212:215], v[220:223], v[54:57]
	v_mfma_f32_16x16x32_bf16 v[50:53], v[216:219], v[220:223], v[50:53]
	ds_read_b128 v[220:223], v192 offset:12288
	s_waitcnt lgkmcnt(1)
	v_mfma_f32_16x16x32_bf16 v[46:49], v[204:207], v[198:201], v[46:49]
	v_mfma_f32_16x16x32_bf16 v[42:45], v[208:211], v[198:201], v[42:45]
	v_mfma_f32_16x16x32_bf16 v[38:41], v[212:215], v[198:201], v[38:41]
	v_mfma_f32_16x16x32_bf16 v[34:37], v[216:219], v[198:201], v[34:37]
	ds_read_b128 v[198:201], v192 offset:14336
	s_waitcnt lgkmcnt(1)
	v_mfma_f32_16x16x32_bf16 v[30:33], v[204:207], v[220:223], v[30:33]
	v_mfma_f32_16x16x32_bf16 v[26:29], v[208:211], v[220:223], v[26:29]
	v_mfma_f32_16x16x32_bf16 v[22:25], v[212:215], v[220:223], v[22:25]
	v_mfma_f32_16x16x32_bf16 v[18:21], v[216:219], v[220:223], v[18:21]
	s_waitcnt lgkmcnt(0)
	v_mfma_f32_16x16x32_bf16 v[14:17], v[204:207], v[198:201], v[14:17]
	v_mfma_f32_16x16x32_bf16 v[10:13], v[208:211], v[198:201], v[10:13]
	v_mfma_f32_16x16x32_bf16 v[6:9], v[212:215], v[198:201], v[6:9]
	v_mfma_f32_16x16x32_bf16 v[2:5], v[216:219], v[198:201], v[2:5]
	s_cmpk_eq_i32 s16, 0x1580
	s_waitcnt vmcnt(0)
	s_barrier
; #define MFMA16(a, b, c) __builtin_amdgcn_mfma_f32_16x16x32_bf16((a), (b), (c), 0, 0, 0)
;     ...
;   for (int kt = 0; kt < nk; ++kt) {
;     const int buf = kt & 1;
;     const char* cA = smem + buf * STAGE + (wm * 32 * MI + r16) * 128;
;     const char* cB = smem + buf * STAGE + 32768 + (wn * 64 + r16) * 128;
; #pragma unroll
;     for (int k2 = 0; k2 < 2; ++k2) {
;       if (k2 == 1 && kt + 1 < nk) STAGE_TILE(buf ^ 1, (kt + 1) * 64)
;       const int po = ((4 * k2 + q4) ^ swz) * 16;
;       bf16x8 bf[4];
; #pragma unroll
;       for (int nt = 0; nt < 4; ++nt) bf[nt] = *(const bf16x8*)(cB + nt * 16 * 128 + po);
;       bf16x8 afc = *(const bf16x8*)(cA + po);
; #pragma unroll
;       for (int a = 0; a < MT; ++a) {
;         bf16x8 afn = afc;
;         if (a + 1 < MT) afn = *(const bf16x8*)(cA + (a + 1) * 16 * 128 + po);
;         __builtin_amdgcn_sched_barrier(0);
; #pragma unroll
;         for (int nt = 0; nt < 4; ++nt) acc[a][nt] = MFMA16(bf[nt], afc, acc[a][nt]);
;         __builtin_amdgcn_sched_barrier(0);
;         afc = afn;
;       }
;     }
;     asm volatile("s_waitcnt vmcnt(0)" ::: "memory");
;     __syncthreads();
;   }
	s_cbranch_scc0 .LBB0_48
	s_add_i32 s16, 0, 0x10000
	v_add_u32_e32 v138, s16, v148
	v_readlane_b32 s16, v254, 18
	s_nop 1
	v_add_u32_e32 v139, s16, v147
	v_add_u32_e32 v145, v139, v146
	ds_read_b128 v[130:133], v145
	ds_read_b128 v[134:137], v145 offset:2048
	ds_read_b128 v[148:151], v145 offset:4096
	ds_read_b128 v[152:155], v145 offset:6144
	v_add_u32_e32 v145, v138, v146
	ds_read_b128 v[156:159], v145
	ds_read_b128 v[160:163], v145 offset:2048
	s_waitcnt lgkmcnt(1)
	v_mfma_f32_16x16x32_bf16 v[126:129], v[130:133], v[156:159], v[126:129]
	v_mfma_f32_16x16x32_bf16 v[122:125], v[134:137], v[156:159], v[122:125]
	v_mfma_f32_16x16x32_bf16 v[118:121], v[148:151], v[156:159], v[118:121]
	v_mfma_f32_16x16x32_bf16 v[114:117], v[152:155], v[156:159], v[114:117]
	ds_read_b128 v[156:159], v145 offset:4096
	s_waitcnt lgkmcnt(1)
	v_mfma_f32_16x16x32_bf16 v[110:113], v[130:133], v[160:163], v[110:113]
	v_mfma_f32_16x16x32_bf16 v[106:109], v[134:137], v[160:163], v[106:109]
	v_mfma_f32_16x16x32_bf16 v[102:105], v[148:151], v[160:163], v[102:105]
	v_mfma_f32_16x16x32_bf16 v[98:101], v[152:155], v[160:163], v[98:101]
	ds_read_b128 v[160:163], v145 offset:6144
	s_waitcnt lgkmcnt(1)
	v_mfma_f32_16x16x32_bf16 v[94:97], v[130:133], v[156:159], v[94:97]
	v_mfma_f32_16x16x32_bf16 v[90:93], v[134:137], v[156:159], v[90:93]
	v_mfma_f32_16x16x32_bf16 v[86:89], v[148:151], v[156:159], v[86:89]
	v_mfma_f32_16x16x32_bf16 v[82:85], v[152:155], v[156:159], v[82:85]
	ds_read_b128 v[156:159], v145 offset:8192
	s_waitcnt lgkmcnt(1)
	v_mfma_f32_16x16x32_bf16 v[78:81], v[130:133], v[160:163], v[78:81]
	v_mfma_f32_16x16x32_bf16 v[74:77], v[134:137], v[160:163], v[74:77]
	v_mfma_f32_16x16x32_bf16 v[70:73], v[148:151], v[160:163], v[70:73]
	v_mfma_f32_16x16x32_bf16 v[66:69], v[152:155], v[160:163], v[66:69]
	ds_read_b128 v[160:163], v145 offset:10240
	s_waitcnt lgkmcnt(1)
	v_mfma_f32_16x16x32_bf16 v[62:65], v[130:133], v[156:159], v[62:65]
	v_mfma_f32_16x16x32_bf16 v[58:61], v[134:137], v[156:159], v[58:61]
	v_mfma_f32_16x16x32_bf16 v[54:57], v[148:151], v[156:159], v[54:57]
	v_mfma_f32_16x16x32_bf16 v[50:53], v[152:155], v[156:159], v[50:53]
	ds_read_b128 v[156:159], v145 offset:12288
	s_waitcnt lgkmcnt(1)
	v_mfma_f32_16x16x32_bf16 v[46:49], v[130:133], v[160:163], v[46:49]
	v_mfma_f32_16x16x32_bf16 v[42:45], v[134:137], v[160:163], v[42:45]
	v_mfma_f32_16x16x32_bf16 v[38:41], v[148:151], v[160:163], v[38:41]
	v_mfma_f32_16x16x32_bf16 v[34:37], v[152:155], v[160:163], v[34:37]
	ds_read_b128 v[160:163], v145 offset:14336
	s_waitcnt lgkmcnt(1)
	v_mfma_f32_16x16x32_bf16 v[30:33], v[130:133], v[156:159], v[30:33]
	v_mfma_f32_16x16x32_bf16 v[26:29], v[134:137], v[156:159], v[26:29]
	v_mfma_f32_16x16x32_bf16 v[22:25], v[148:151], v[156:159], v[22:25]
	v_mfma_f32_16x16x32_bf16 v[18:21], v[152:155], v[156:159], v[18:21]
	s_waitcnt lgkmcnt(0)
	v_mfma_f32_16x16x32_bf16 v[14:17], v[130:133], v[160:163], v[14:17]
	v_mfma_f32_16x16x32_bf16 v[10:13], v[134:137], v[160:163], v[10:13]
	v_mfma_f32_16x16x32_bf16 v[6:9], v[148:151], v[160:163], v[6:9]
	v_mfma_f32_16x16x32_bf16 v[2:5], v[152:155], v[160:163], v[2:5]
	v_add_u32_e32 v139, v139, v144
	ds_read_b128 v[130:133], v139
	ds_read_b128 v[134:137], v139 offset:2048
	ds_read_b128 v[146:149], v139 offset:4096
	ds_read_b128 v[150:153], v139 offset:6144
	v_add_u32_e32 v138, v138, v144
	ds_read_b128 v[154:157], v138
	ds_read_b128 v[158:161], v138 offset:2048
	s_waitcnt lgkmcnt(1)
	v_mfma_f32_16x16x32_bf16 v[126:129], v[130:133], v[154:157], v[126:129]
	v_mfma_f32_16x16x32_bf16 v[122:125], v[134:137], v[154:157], v[122:125]
	v_mfma_f32_16x16x32_bf16 v[118:121], v[146:149], v[154:157], v[118:121]
	v_mfma_f32_16x16x32_bf16 v[114:117], v[150:153], v[154:157], v[114:117]
	ds_read_b128 v[154:157], v138 offset:4096
	s_waitcnt lgkmcnt(1)
	v_mfma_f32_16x16x32_bf16 v[110:113], v[130:133], v[158:161], v[110:113]
	v_mfma_f32_16x16x32_bf16 v[106:109], v[134:137], v[158:161], v[106:109]
	v_mfma_f32_16x16x32_bf16 v[102:105], v[146:149], v[158:161], v[102:105]
	v_mfma_f32_16x16x32_bf16 v[98:101], v[150:153], v[158:161], v[98:101]
	ds_read_b128 v[158:161], v138 offset:6144
	s_waitcnt lgkmcnt(1)
	v_mfma_f32_16x16x32_bf16 v[94:97], v[130:133], v[154:157], v[94:97]
	v_mfma_f32_16x16x32_bf16 v[90:93], v[134:137], v[154:157], v[90:93]
	v_mfma_f32_16x16x32_bf16 v[86:89], v[146:149], v[154:157], v[86:89]
	v_mfma_f32_16x16x32_bf16 v[82:85], v[150:153], v[154:157], v[82:85]
	ds_read_b128 v[154:157], v138 offset:8192
	s_waitcnt lgkmcnt(1)
	v_mfma_f32_16x16x32_bf16 v[78:81], v[130:133], v[158:161], v[78:81]
	v_mfma_f32_16x16x32_bf16 v[74:77], v[134:137], v[158:161], v[74:77]
	v_mfma_f32_16x16x32_bf16 v[70:73], v[146:149], v[158:161], v[70:73]
	v_mfma_f32_16x16x32_bf16 v[66:69], v[150:153], v[158:161], v[66:69]
	ds_read_b128 v[158:161], v138 offset:10240
	s_waitcnt lgkmcnt(1)
	v_mfma_f32_16x16x32_bf16 v[62:65], v[130:133], v[154:157], v[62:65]
	v_mfma_f32_16x16x32_bf16 v[58:61], v[134:137], v[154:157], v[58:61]
	v_mfma_f32_16x16x32_bf16 v[54:57], v[146:149], v[154:157], v[54:57]
	v_mfma_f32_16x16x32_bf16 v[50:53], v[150:153], v[154:157], v[50:53]
	ds_read_b128 v[154:157], v138 offset:12288
	s_waitcnt lgkmcnt(1)
	v_mfma_f32_16x16x32_bf16 v[46:49], v[130:133], v[158:161], v[46:49]
	v_mfma_f32_16x16x32_bf16 v[42:45], v[134:137], v[158:161], v[42:45]
	v_mfma_f32_16x16x32_bf16 v[38:41], v[146:149], v[158:161], v[38:41]
	v_mfma_f32_16x16x32_bf16 v[34:37], v[150:153], v[158:161], v[34:37]
	ds_read_b128 v[158:161], v138 offset:14336
	s_waitcnt lgkmcnt(1)
;     ...
;   const int row0 = m0 + wm * 32 * MI + r16, cbw = n0 + wn * 64;
;   if constexpr (std::is_invocable_v<EP, int, int, int, const f32x4&, const f32x4&, const f32x4&, const f32x4&>) {
; #pragma unroll
;     for (int a = 0; a < MT; ++a) ep(row0 + 16 * a, cbw, q4, acc[a][0], acc[a][1], acc[a][2], acc[a][3]);
;   } else {
; #pragma unroll
;     for (int a = 0; a < MT; ++a)
; #pragma unroll
;       for (int nt = 0; nt < 4; ++nt)
;         ep(row0 + 16 * a, cbw + 16 * nt + 4 * q4, acc[a][nt][0], acc[a][nt][1], acc[a][nt][2], acc[a][nt][3]);
; DI void phase_resid(char* smem, const Params& p, int layer, const bf16_t* A, int K, const bf16_t* W, int gate_idx, bool first) {
;     ...
;   auto ep = [&](int row, int col, float v0, float v1, float v2, float v3) {
;     const int b = row / TT, t = row - b * TT;
;     const float4 g = *(const float4*)(p.mod + (size_t)(layer * 5 + (t < CTXL ? 4 : b)) * 6144 + gate_idx * 1024 + col);
;     const float4 xo = *(const float4*)(xsrc_row(p, first, row) + col);
;     *(float4*)(xdst_row(p, row) + col) = make_float4(xo.x + g.x * v0, xo.y + g.y * v1, xo.z + g.z * v2, xo.w + g.w * v3);
;   };
	v_mfma_f32_16x16x32_bf16 v[30:33], v[130:133], v[154:157], v[30:33]
	v_mfma_f32_16x16x32_bf16 v[26:29], v[134:137], v[154:157], v[26:29]
	v_mfma_f32_16x16x32_bf16 v[22:25], v[146:149], v[154:157], v[22:25]
	v_mfma_f32_16x16x32_bf16 v[18:21], v[150:153], v[154:157], v[18:21]
	s_waitcnt lgkmcnt(0)
	v_mfma_f32_16x16x32_bf16 v[14:17], v[130:133], v[158:161], v[14:17]
	v_mfma_f32_16x16x32_bf16 v[10:13], v[134:137], v[158:161], v[10:13]
	v_mfma_f32_16x16x32_bf16 v[6:9], v[146:149], v[158:161], v[6:9]
	v_mfma_f32_16x16x32_bf16 v[2:5], v[150:153], v[158:161], v[2:5]
	v_or_b32_e32 v131, s40, v142
	v_lshlrev_b32_e32 v130, 6, v143
	v_lshl_add_u32 v142, v140, 7, v131
	v_lshlrev_b32_e32 v131, 2, v141
	v_or3_b32 v134, v130, v131, s39
	v_mul_hi_i32 v130, v142, s1
	v_lshrrev_b32_e32 v131, 31, v130
	v_ashrrev_i32_e32 v130, 11, v130
	v_add_u32_e32 v130, v130, v131
	v_mad_i32_i24 v131, v130, s90, v142
	s_movk_i32 s39, 0x100
	v_cmp_gt_i32_e32 vcc, s39, v131
	v_add_u32_e32 v132, 0xffffff00, v131
	v_ashrrev_i32_e32 v133, 31, v131
	v_readlane_b32 s40, v254, 1
	v_cndmask_b32_e64 v135, v130, 4, vcc
	v_cndmask_b32_e32 v133, 0, v133, vcc
	v_cndmask_b32_e32 v132, v132, v131, vcc
	v_ashrrev_i32_e32 v131, 31, v130
	v_cndmask_b32_e64 v136, 25, 20, vcc
	v_readlane_b32 s41, v254, 2
	v_lshlrev_b64 v[140:141], v136, v[130:131]
	v_lshlrev_b64 v[150:151], 12, v[132:133]
	v_add_u32_e32 v130, s37, v135
	v_mov_b64_e32 v[132:133], s[40:41]
	s_movk_i32 s40, 0x6000
	v_readlane_b32 s42, v254, 3
	v_readlane_b32 s43, v254, 4
	v_mad_i64_i32 v[130:131], s[16:17], v130, s40, v[132:133]
	s_mov_b64 s[42:43], 0x5000
	v_ashrrev_i32_e32 v135, 31, v134
	v_readlane_b32 s16, v252, 26
	v_lshl_add_u64 v[136:137], v[130:131], 0, s[42:43]
	v_lshlrev_b64 v[130:131], 2, v[134:135]
	v_mov_b32_e32 v135, s16
	v_readlane_b32 s16, v252, 28
	s_waitcnt vmcnt(0)
	s_barrier
	s_nop 0
	v_mov_b32_e32 v143, s16
	v_readlane_b32 s16, v252, 25
	v_cndmask_b32_e32 v139, v135, v143, vcc
	s_nop 0
	v_mov_b32_e32 v144, s16
	v_readlane_b32 s16, v252, 27
	v_readlane_b32 s68, v252, 5
	v_readlane_b32 s80, v252, 17
	v_mov_b32_e32 v145, s16
	v_cndmask_b32_e32 v138, v144, v145, vcc
	global_load_dwordx2 v[138:139], v[138:139], off
	v_readlane_b32 s81, v252, 18
	v_readlane_b32 s82, v252, 19
	v_readlane_b32 s83, v252, 20
	v_mov_b32_e32 v146, s81
	v_mov_b32_e32 v148, s80
	v_mov_b32_e32 v147, s83
	v_mov_b32_e32 v149, s82
	v_cndmask_b32_e32 v155, v146, v147, vcc
	v_cndmask_b32_e32 v154, v148, v149, vcc
	v_lshl_add_u64 v[152:153], v[136:137], 0, v[130:131]
	s_add_i32 s38, s38, s30
	s_cmp_gt_i32 s38, 31
	v_readlane_b32 s44, v254, 5
	v_readlane_b32 s45, v254, 6
	v_readlane_b32 s46, v254, 7
	v_readlane_b32 s47, v254, 8
	v_readlane_b32 s48, v254, 9
	v_readlane_b32 s49, v254, 10
	v_readlane_b32 s50, v254, 11
	v_readlane_b32 s51, v254, 12
	v_readlane_b32 s52, v254, 13
	v_readlane_b32 s53, v254, 14
	v_readlane_b32 s54, v254, 15
	v_readlane_b32 s55, v254, 16
	v_readlane_b32 s69, v252, 6
	v_readlane_b32 s70, v252, 7
	v_readlane_b32 s71, v252, 8
	v_readlane_b32 s72, v252, 9
	v_readlane_b32 s73, v252, 10
	v_readlane_b32 s74, v252, 11
	v_readlane_b32 s75, v252, 12
	v_readlane_b32 s76, v252, 13
	v_readlane_b32 s77, v252, 14
	v_readlane_b32 s78, v252, 15
	v_readlane_b32 s79, v252, 16
	s_waitcnt vmcnt(0)
	v_lshl_add_u64 v[138:139], v[138:139], 0, v[140:141]
	v_lshl_add_u64 v[138:139], v[138:139], 0, v[150:151]
	v_lshl_add_u64 v[140:141], v[154:155], 0, v[140:141]
	v_lshl_add_u64 v[138:139], v[138:139], 0, v[130:131]
	v_lshl_add_u64 v[140:141], v[140:141], 0, v[150:151]
	v_lshl_add_u64 v[140:141], v[140:141], 0, v[130:131]
	s_cselect_b64 s[16:17], -1, 0
	global_load_dwordx4 v[156:159], v[152:153], off
	global_load_dwordx4 v[160:163], v[152:153], off offset:64
	global_load_dwordx4 v[164:167], v[152:153], off offset:128
	global_load_dwordx4 v[168:171], v[152:153], off offset:192
	global_load_dwordx4 v[172:175], v[138:139], off
	global_load_dwordx4 v[176:179], v[138:139], off offset:64
	global_load_dwordx4 v[180:183], v[138:139], off offset:128
	global_load_dwordx4 v[184:187], v[138:139], off offset:192
	v_add_co_u32_e32 v138, vcc, 0x10000, v138
	s_nop 1
	v_addc_co_u32_e32 v139, vcc, 0, v139, vcc
	global_load_dwordx4 v[198:201], v[138:139], off
	global_load_dwordx4 v[202:205], v[138:139], off offset:64
	global_load_dwordx4 v[206:209], v[138:139], off offset:128
	global_load_dwordx4 v[210:213], v[138:139], off offset:192
	v_add_co_u32_e32 v138, vcc, 0x10000, v138
	s_nop 1
	v_addc_co_u32_e32 v139, vcc, 0, v139, vcc
	global_load_dwordx4 v[214:217], v[138:139], off
	global_load_dwordx4 v[218:221], v[138:139], off offset:64
	global_load_dwordx4 v[222:225], v[138:139], off offset:128
	global_load_dwordx4 v[142:145], v[138:139], off offset:192
	v_add_co_u32_e32 v138, vcc, 0x10000, v138
	s_nop 1
	v_addc_co_u32_e32 v139, vcc, 0, v139, vcc
	s_waitcnt vmcnt(8)
	v_pk_fma_f32 v[126:127], v[126:127], v[156:157], v[172:173]
	v_pk_fma_f32 v[128:129], v[128:129], v[158:159], v[174:175]
	v_pk_fma_f32 v[122:123], v[122:123], v[160:161], v[176:177]
	v_pk_fma_f32 v[124:125], v[124:125], v[162:163], v[178:179]
	v_pk_fma_f32 v[118:119], v[118:119], v[164:165], v[180:181]
	v_pk_fma_f32 v[120:121], v[120:121], v[166:167], v[182:183]
	v_pk_fma_f32 v[114:115], v[114:115], v[168:169], v[184:185]
	v_pk_fma_f32 v[116:117], v[116:117], v[170:171], v[186:187]
	global_store_dwordx4 v[140:141], v[126:129], off
	global_store_dwordx4 v[140:141], v[122:125], off offset:64
	global_store_dwordx4 v[140:141], v[118:121], off offset:128
	global_store_dwordx4 v[140:141], v[114:117], off offset:192
	v_add_co_u32_e32 v140, vcc, 0x10000, v140
	s_nop 1
	v_addc_co_u32_e32 v141, vcc, 0, v141, vcc
	global_load_dwordx4 v[172:175], v[138:139], off
	global_load_dwordx4 v[176:179], v[138:139], off offset:64
	global_load_dwordx4 v[180:183], v[138:139], off offset:128
	global_load_dwordx4 v[184:187], v[138:139], off offset:192
	v_add_co_u32_e32 v138, vcc, 0x10000, v138
	s_nop 1
	v_addc_co_u32_e32 v139, vcc, 0, v139, vcc
	s_waitcnt vmcnt(12)
;     ...
; #pragma unroll
;     for (int a = 0; a < MT; ++a)
; #pragma unroll
;       for (int nt = 0; nt < 4; ++nt)
;         ep(row0 + 16 * a, cbw + 16 * nt + 4 * q4, acc[a][nt][0], acc[a][nt][1], acc[a][nt][2], acc[a][nt][3]);
; DI void phase_resid(char* smem, const Params& p, int layer, const bf16_t* A, int K, const bf16_t* W, int gate_idx, bool first) {
;     ...
;   auto ep = [&](int row, int col, float v0, float v1, float v2, float v3) {
;     const int b = row / TT, t = row - b * TT;
;     const float4 g = *(const float4*)(p.mod + (size_t)(layer * 5 + (t < CTXL ? 4 : b)) * 6144 + gate_idx * 1024 + col);
;     const float4 xo = *(const float4*)(xsrc_row(p, first, row) + col);
;     *(float4*)(xdst_row(p, row) + col) = make_float4(xo.x + g.x * v0, xo.y + g.y * v1, xo.z + g.z * v2, xo.w + g.w * v3);
;   };
	v_pk_fma_f32 v[110:111], v[110:111], v[156:157], v[198:199]
	v_pk_fma_f32 v[112:113], v[112:113], v[158:159], v[200:201]
	v_pk_fma_f32 v[106:107], v[106:107], v[160:161], v[202:203]
	v_pk_fma_f32 v[108:109], v[108:109], v[162:163], v[204:205]
	v_pk_fma_f32 v[102:103], v[102:103], v[164:165], v[206:207]
	v_pk_fma_f32 v[104:105], v[104:105], v[166:167], v[208:209]
	v_pk_fma_f32 v[98:99], v[98:99], v[168:169], v[210:211]
	v_pk_fma_f32 v[100:101], v[100:101], v[170:171], v[212:213]
	global_store_dwordx4 v[140:141], v[110:113], off
	global_store_dwordx4 v[140:141], v[106:109], off offset:64
	global_store_dwordx4 v[140:141], v[102:105], off offset:128
	global_store_dwordx4 v[140:141], v[98:101], off offset:192
	v_add_co_u32_e32 v140, vcc, 0x10000, v140
	s_nop 1
	v_addc_co_u32_e32 v141, vcc, 0, v141, vcc
	global_load_dwordx4 v[198:201], v[138:139], off
	global_load_dwordx4 v[202:205], v[138:139], off offset:64
	global_load_dwordx4 v[206:209], v[138:139], off offset:128
	global_load_dwordx4 v[210:213], v[138:139], off offset:192
	v_add_co_u32_e32 v138, vcc, 0x10000, v138
	s_nop 1
	v_addc_co_u32_e32 v139, vcc, 0, v139, vcc
	s_waitcnt vmcnt(16)
	v_pk_fma_f32 v[94:95], v[94:95], v[156:157], v[214:215]
	v_pk_fma_f32 v[96:97], v[96:97], v[158:159], v[216:217]
	v_pk_fma_f32 v[90:91], v[90:91], v[160:161], v[218:219]
	v_pk_fma_f32 v[92:93], v[92:93], v[162:163], v[220:221]
	v_pk_fma_f32 v[86:87], v[86:87], v[164:165], v[222:223]
	v_pk_fma_f32 v[88:89], v[88:89], v[166:167], v[224:225]
	v_pk_fma_f32 v[82:83], v[82:83], v[168:169], v[142:143]
	v_pk_fma_f32 v[84:85], v[84:85], v[170:171], v[144:145]
	global_store_dwordx4 v[140:141], v[94:97], off
	global_store_dwordx4 v[140:141], v[90:93], off offset:64
	global_store_dwordx4 v[140:141], v[86:89], off offset:128
	global_store_dwordx4 v[140:141], v[82:85], off offset:192
	v_add_co_u32_e32 v140, vcc, 0x10000, v140
	s_nop 1
	v_addc_co_u32_e32 v141, vcc, 0, v141, vcc
	global_load_dwordx4 v[214:217], v[138:139], off
	global_load_dwordx4 v[218:221], v[138:139], off offset:64
	global_load_dwordx4 v[222:225], v[138:139], off offset:128
	global_load_dwordx4 v[142:145], v[138:139], off offset:192
	v_add_co_u32_e32 v138, vcc, 0x10000, v138
	s_nop 1
	v_addc_co_u32_e32 v139, vcc, 0, v139, vcc
	s_waitcnt vmcnt(16)
	v_pk_fma_f32 v[78:79], v[78:79], v[156:157], v[172:173]
	v_pk_fma_f32 v[80:81], v[80:81], v[158:159], v[174:175]
	v_pk_fma_f32 v[74:75], v[74:75], v[160:161], v[176:177]
	v_pk_fma_f32 v[76:77], v[76:77], v[162:163], v[178:179]
	v_pk_fma_f32 v[70:71], v[70:71], v[164:165], v[180:181]
	v_pk_fma_f32 v[72:73], v[72:73], v[166:167], v[182:183]
	v_pk_fma_f32 v[66:67], v[66:67], v[168:169], v[184:185]
	v_pk_fma_f32 v[68:69], v[68:69], v[170:171], v[186:187]
	global_store_dwordx4 v[140:141], v[78:81], off
	global_store_dwordx4 v[140:141], v[74:77], off offset:64
	global_store_dwordx4 v[140:141], v[70:73], off offset:128
	global_store_dwordx4 v[140:141], v[66:69], off offset:192
	v_add_co_u32_e32 v140, vcc, 0x10000, v140
	s_nop 1
	v_addc_co_u32_e32 v141, vcc, 0, v141, vcc
	global_load_dwordx4 v[172:175], v[138:139], off
	global_load_dwordx4 v[176:179], v[138:139], off offset:64
	global_load_dwordx4 v[180:183], v[138:139], off offset:128
	global_load_dwordx4 v[184:187], v[138:139], off offset:192
	v_add_co_u32_e32 v138, vcc, 0x10000, v138
	s_nop 1
	v_addc_co_u32_e32 v139, vcc, 0, v139, vcc
	s_waitcnt vmcnt(16)
	v_pk_fma_f32 v[62:63], v[62:63], v[156:157], v[198:199]
	v_pk_fma_f32 v[64:65], v[64:65], v[158:159], v[200:201]
	v_pk_fma_f32 v[58:59], v[58:59], v[160:161], v[202:203]
	v_pk_fma_f32 v[60:61], v[60:61], v[162:163], v[204:205]
	v_pk_fma_f32 v[54:55], v[54:55], v[164:165], v[206:207]
	v_pk_fma_f32 v[56:57], v[56:57], v[166:167], v[208:209]
	v_pk_fma_f32 v[50:51], v[50:51], v[168:169], v[210:211]
	v_pk_fma_f32 v[52:53], v[52:53], v[170:171], v[212:213]
	global_store_dwordx4 v[140:141], v[62:65], off
	global_store_dwordx4 v[140:141], v[58:61], off offset:64
	global_store_dwordx4 v[140:141], v[54:57], off offset:128
	global_store_dwordx4 v[140:141], v[50:53], off offset:192
	v_add_co_u32_e32 v140, vcc, 0x10000, v140
	s_nop 1
	v_addc_co_u32_e32 v141, vcc, 0, v141, vcc
	global_load_dwordx4 v[198:201], v[138:139], off
	global_load_dwordx4 v[202:205], v[138:139], off offset:64
	global_load_dwordx4 v[206:209], v[138:139], off offset:128
	global_load_dwordx4 v[210:213], v[138:139], off offset:192
	s_waitcnt vmcnt(16)
	v_pk_fma_f32 v[46:47], v[46:47], v[156:157], v[214:215]
	v_pk_fma_f32 v[48:49], v[48:49], v[158:159], v[216:217]
	v_pk_fma_f32 v[42:43], v[42:43], v[160:161], v[218:219]
	v_pk_fma_f32 v[44:45], v[44:45], v[162:163], v[220:221]
	v_pk_fma_f32 v[38:39], v[38:39], v[164:165], v[222:223]
	v_pk_fma_f32 v[40:41], v[40:41], v[166:167], v[224:225]
	v_pk_fma_f32 v[34:35], v[34:35], v[168:169], v[142:143]
	v_pk_fma_f32 v[36:37], v[36:37], v[170:171], v[144:145]
	global_store_dwordx4 v[140:141], v[46:49], off
	global_store_dwordx4 v[140:141], v[42:45], off offset:64
	global_store_dwordx4 v[140:141], v[38:41], off offset:128
	global_store_dwordx4 v[140:141], v[34:37], off offset:192
	v_add_co_u32_e32 v140, vcc, 0x10000, v140
	s_nop 1
	v_addc_co_u32_e32 v141, vcc, 0, v141, vcc
	s_waitcnt vmcnt(12)
	v_pk_fma_f32 v[30:31], v[30:31], v[156:157], v[172:173]
	v_pk_fma_f32 v[32:33], v[32:33], v[158:159], v[174:175]
	v_pk_fma_f32 v[26:27], v[26:27], v[160:161], v[176:177]
	v_pk_fma_f32 v[28:29], v[28:29], v[162:163], v[178:179]
	v_pk_fma_f32 v[22:23], v[22:23], v[164:165], v[180:181]
	v_pk_fma_f32 v[24:25], v[24:25], v[166:167], v[182:183]
	v_pk_fma_f32 v[18:19], v[18:19], v[168:169], v[184:185]
	v_pk_fma_f32 v[20:21], v[20:21], v[170:171], v[186:187]
	global_store_dwordx4 v[140:141], v[30:33], off
	global_store_dwordx4 v[140:141], v[26:29], off offset:64
	global_store_dwordx4 v[140:141], v[22:25], off offset:128
	global_store_dwordx4 v[140:141], v[18:21], off offset:192
	v_add_co_u32_e32 v140, vcc, 0x10000, v140
	s_nop 1
	v_addc_co_u32_e32 v141, vcc, 0, v141, vcc
	s_waitcnt vmcnt(8)
	v_pk_fma_f32 v[14:15], v[14:15], v[156:157], v[198:199]
	v_pk_fma_f32 v[16:17], v[16:17], v[158:159], v[200:201]
	v_pk_fma_f32 v[10:11], v[10:11], v[160:161], v[202:203]
	v_pk_fma_f32 v[12:13], v[12:13], v[162:163], v[204:205]
	v_pk_fma_f32 v[6:7], v[6:7], v[164:165], v[206:207]
	v_pk_fma_f32 v[8:9], v[8:9], v[166:167], v[208:209]
	v_pk_fma_f32 v[2:3], v[2:3], v[168:169], v[210:211]
	v_pk_fma_f32 v[4:5], v[4:5], v[170:171], v[212:213]
	global_store_dwordx4 v[140:141], v[14:17], off
	global_store_dwordx4 v[140:141], v[10:13], off offset:64
	global_store_dwordx4 v[140:141], v[6:9], off offset:128
	global_store_dwordx4 v[140:141], v[2:5], off offset:192
	s_branch .LBB0_41

; #define MFMA16(a, b, c) __builtin_amdgcn_mfma_f32_16x16x32_bf16((a), (b), (c), 0, 0, 0)
;     ...
;   for (int kt = 0; kt < nk; ++kt) {
;     const int buf = kt & 1;
;     const char* cA = smem + buf * STAGE + (wm * 32 * MI + r16) * 128;
;     const char* cB = smem + buf * STAGE + 32768 + (wn * 64 + r16) * 128;
; #pragma unroll
;     for (int k2 = 0; k2 < 2; ++k2) {
;       if (k2 == 1 && kt + 1 < nk) STAGE_TILE(buf ^ 1, (kt + 1) * 64)
;       const int po = ((4 * k2 + q4) ^ swz) * 16;
;       bf16x8 bf[4];
; #pragma unroll
;       for (int nt = 0; nt < 4; ++nt) bf[nt] = *(const bf16x8*)(cB + nt * 16 * 128 + po);
;       bf16x8 afc = *(const bf16x8*)(cA + po);
; #pragma unroll
;       for (int a = 0; a < MT; ++a) {
;         bf16x8 afn = afc;
;         if (a + 1 < MT) afn = *(const bf16x8*)(cA + (a + 1) * 16 * 128 + po);
;         __builtin_amdgcn_sched_barrier(0);
; #pragma unroll
;         for (int nt = 0; nt < 4; ++nt) acc[a][nt] = MFMA16(bf[nt], afc, acc[a][nt]);
;         __builtin_amdgcn_sched_barrier(0);
;         afc = afn;
;       }
;     }
;     asm volatile("s_waitcnt vmcnt(0)" ::: "memory");
;     __syncthreads();
;   }
.LBB0_75:
	s_and_b32 s41, s40, 0x10000
	s_add_i32 s42, s41, 0
	v_add_u32_e32 v190, s42, v147
	v_add_u32_e32 v162, v190, v146
	v_add_u32_e32 v149, s42, v148
	ds_read_b128 v[150:153], v162 offset:32768
	ds_read_b128 v[154:157], v162 offset:34816
	ds_read_b128 v[158:161], v162 offset:36864
	ds_read_b128 v[162:165], v162 offset:38912
	v_add_u32_e32 v202, v149, v146
	ds_read_b128 v[166:169], v202
	ds_read_b128 v[170:173], v202 offset:2048
	s_xor_b32 s41, s41, 0x10000
	s_waitcnt lgkmcnt(1)
	v_mfma_f32_16x16x32_bf16 v[126:129], v[150:153], v[166:169], v[126:129]
	v_readfirstlane_b32 s42, v145
	v_mfma_f32_16x16x32_bf16 v[122:125], v[154:157], v[166:169], v[122:125]
	s_nop 0
	v_mfma_f32_16x16x32_bf16 v[118:121], v[158:161], v[166:169], v[118:121]
	s_add_u32 s42, s42, s41
	v_mfma_f32_16x16x32_bf16 v[114:117], v[162:165], v[166:169], v[114:117]
	ds_read_b128 v[166:169], v202 offset:4096
	s_add_u32 m0, s42, 0x0
	s_waitcnt lgkmcnt(1)
	v_mfma_f32_16x16x32_bf16 v[110:113], v[150:153], v[170:173], v[110:113]
	global_load_lds_dwordx4 v174, s[100:101]
	v_mfma_f32_16x16x32_bf16 v[106:109], v[154:157], v[170:173], v[106:109]
	s_add_u32 m0, s42, 0x2000
	v_mfma_f32_16x16x32_bf16 v[102:105], v[158:161], v[170:173], v[102:105]
	global_load_lds_dwordx4 v175, s[100:101]
	v_mfma_f32_16x16x32_bf16 v[98:101], v[162:165], v[170:173], v[98:101]
	ds_read_b128 v[170:173], v202 offset:6144
	s_add_u32 m0, s42, 0x4000
	s_waitcnt lgkmcnt(1)
	v_mfma_f32_16x16x32_bf16 v[94:97], v[150:153], v[166:169], v[94:97]
	global_load_lds_dwordx4 v176, s[100:101]
	v_mfma_f32_16x16x32_bf16 v[90:93], v[154:157], v[166:169], v[90:93]
	s_add_u32 m0, s42, 0x6000
	v_mfma_f32_16x16x32_bf16 v[86:89], v[158:161], v[166:169], v[86:89]
	global_load_lds_dwordx4 v177, s[100:101]
	v_mfma_f32_16x16x32_bf16 v[82:85], v[162:165], v[166:169], v[82:85]
	ds_read_b128 v[166:169], v202 offset:8192
	s_add_u32 m0, s42, 0x8000
	s_waitcnt lgkmcnt(1)
	v_mfma_f32_16x16x32_bf16 v[78:81], v[150:153], v[170:173], v[78:81]
	global_load_lds_dwordx4 v178, s[100:101]
	v_mfma_f32_16x16x32_bf16 v[74:77], v[154:157], v[170:173], v[74:77]
	s_add_u32 m0, s42, 0xa000
	v_mfma_f32_16x16x32_bf16 v[70:73], v[158:161], v[170:173], v[70:73]
	global_load_lds_dwordx4 v179, s[100:101]
	v_mfma_f32_16x16x32_bf16 v[66:69], v[162:165], v[170:173], v[66:69]
	ds_read_b128 v[170:173], v202 offset:10240
	s_add_u32 m0, s42, 0xc000
	s_waitcnt lgkmcnt(1)
	v_mfma_f32_16x16x32_bf16 v[62:65], v[150:153], v[166:169], v[62:65]
	global_load_lds_dwordx4 v180, s[100:101]
	v_mfma_f32_16x16x32_bf16 v[58:61], v[154:157], v[166:169], v[58:61]
	s_add_u32 m0, s42, 0xe000
	v_mfma_f32_16x16x32_bf16 v[54:57], v[158:161], v[166:169], v[54:57]
	global_load_lds_dwordx4 v181, s[100:101]
	v_mfma_f32_16x16x32_bf16 v[50:53], v[162:165], v[166:169], v[50:53]
	ds_read_b128 v[166:169], v202 offset:12288
	v_add_u32_e32 v203, v190, v144
	s_waitcnt lgkmcnt(1)
	v_mfma_f32_16x16x32_bf16 v[46:49], v[150:153], v[170:173], v[46:49]
	v_add_u32_e32 v192, v149, v144
	v_mfma_f32_16x16x32_bf16 v[42:45], v[154:157], v[170:173], v[42:45]
	ds_read_b128 v[204:207], v203 offset:32768
	v_mfma_f32_16x16x32_bf16 v[38:41], v[158:161], v[170:173], v[38:41]
	ds_read_b128 v[208:211], v203 offset:34816
	v_mfma_f32_16x16x32_bf16 v[34:37], v[162:165], v[170:173], v[34:37]
	ds_read_b128 v[170:173], v202 offset:14336
	ds_read_b128 v[212:215], v203 offset:36864
	s_waitcnt lgkmcnt(4)
	v_mfma_f32_16x16x32_bf16 v[30:33], v[150:153], v[166:169], v[30:33]
	ds_read_b128 v[216:219], v203 offset:38912
	v_mfma_f32_16x16x32_bf16 v[26:29], v[154:157], v[166:169], v[26:29]
	ds_read_b128 v[220:223], v192
	v_mfma_f32_16x16x32_bf16 v[22:25], v[158:161], v[166:169], v[22:25]
	ds_read_b128 v[198:201], v192 offset:2048
	v_mfma_f32_16x16x32_bf16 v[18:21], v[162:165], v[166:169], v[18:21]
	s_waitcnt lgkmcnt(4)
	v_mfma_f32_16x16x32_bf16 v[14:17], v[150:153], v[170:173], v[14:17]
	v_mfma_f32_16x16x32_bf16 v[10:13], v[154:157], v[170:173], v[10:13]
	v_mfma_f32_16x16x32_bf16 v[6:9], v[158:161], v[170:173], v[6:9]
	v_mfma_f32_16x16x32_bf16 v[2:5], v[162:165], v[170:173], v[2:5]
	s_waitcnt lgkmcnt(1)
	v_mfma_f32_16x16x32_bf16 v[126:129], v[204:207], v[220:223], v[126:129]
	s_add_u32 s100, s100, 0x80
	v_mfma_f32_16x16x32_bf16 v[122:125], v[208:211], v[220:223], v[122:125]
	s_addc_u32 s101, s101, 0
	v_mfma_f32_16x16x32_bf16 v[118:121], v[212:215], v[220:223], v[118:121]
	s_add_u32 s16, s16, 0x80
	v_mfma_f32_16x16x32_bf16 v[114:117], v[216:219], v[220:223], v[114:117]
	ds_read_b128 v[220:223], v192 offset:4096
	s_waitcnt lgkmcnt(1)
	v_mfma_f32_16x16x32_bf16 v[110:113], v[204:207], v[198:201], v[110:113]
	s_addc_u32 s17, s17, 0
	v_mfma_f32_16x16x32_bf16 v[106:109], v[208:211], v[198:201], v[106:109]
	s_add_i32 s40, s40, 0x10000
	v_mfma_f32_16x16x32_bf16 v[102:105], v[212:215], v[198:201], v[102:105]
	v_mfma_f32_16x16x32_bf16 v[98:101], v[216:219], v[198:201], v[98:101]
	ds_read_b128 v[198:201], v192 offset:6144
	s_waitcnt lgkmcnt(1)
	v_mfma_f32_16x16x32_bf16 v[94:97], v[204:207], v[220:223], v[94:97]
	v_mfma_f32_16x16x32_bf16 v[90:93], v[208:211], v[220:223], v[90:93]
	v_mfma_f32_16x16x32_bf16 v[86:89], v[212:215], v[220:223], v[86:89]
	v_mfma_f32_16x16x32_bf16 v[82:85], v[216:219], v[220:223], v[82:85]
	ds_read_b128 v[220:223], v192 offset:8192
	s_waitcnt lgkmcnt(1)
	v_mfma_f32_16x16x32_bf16 v[78:81], v[204:207], v[198:201], v[78:81]
	v_mfma_f32_16x16x32_bf16 v[74:77], v[208:211], v[198:201], v[74:77]
	v_mfma_f32_16x16x32_bf16 v[70:73], v[212:215], v[198:201], v[70:73]
	v_mfma_f32_16x16x32_bf16 v[66:69], v[216:219], v[198:201], v[66:69]
	ds_read_b128 v[198:201], v192 offset:10240
	s_waitcnt lgkmcnt(1)
	v_mfma_f32_16x16x32_bf16 v[62:65], v[204:207], v[220:223], v[62:65]
	v_mfma_f32_16x16x32_bf16 v[58:61], v[208:211], v[220:223], v[58:61]
	v_mfma_f32_16x16x32_bf16 v[54:57], v[212:215], v[220:223], v[54:57]
	v_mfma_f32_16x16x32_bf16 v[50:53], v[216:219], v[220:223], v[50:53]
	ds_read_b128 v[220:223], v192 offset:12288
	s_waitcnt lgkmcnt(1)
	v_mfma_f32_16x16x32_bf16 v[46:49], v[204:207], v[198:201], v[46:49]
	v_mfma_f32_16x16x32_bf16 v[42:45], v[208:211], v[198:201], v[42:45]
	v_mfma_f32_16x16x32_bf16 v[38:41], v[212:215], v[198:201], v[38:41]
	v_mfma_f32_16x16x32_bf16 v[34:37], v[216:219], v[198:201], v[34:37]
	ds_read_b128 v[198:201], v192 offset:14336
	s_waitcnt lgkmcnt(1)
	v_mfma_f32_16x16x32_bf16 v[30:33], v[204:207], v[220:223], v[30:33]
	v_mfma_f32_16x16x32_bf16 v[26:29], v[208:211], v[220:223], v[26:29]
	v_mfma_f32_16x16x32_bf16 v[22:25], v[212:215], v[220:223], v[22:25]
	v_mfma_f32_16x16x32_bf16 v[18:21], v[216:219], v[220:223], v[18:21]
	s_waitcnt lgkmcnt(0)
	v_mfma_f32_16x16x32_bf16 v[14:17], v[204:207], v[198:201], v[14:17]
	v_mfma_f32_16x16x32_bf16 v[10:13], v[208:211], v[198:201], v[10:13]
	v_mfma_f32_16x16x32_bf16 v[6:9], v[212:215], v[198:201], v[6:9]
	v_mfma_f32_16x16x32_bf16 v[2:5], v[216:219], v[198:201], v[2:5]
	s_cmpk_lg_i32 s16, 0x780
	s_waitcnt vmcnt(0)
	s_barrier
; #define MFMA16(a, b, c) __builtin_amdgcn_mfma_f32_16x16x32_bf16((a), (b), (c), 0, 0, 0)
;     ...
;   for (int kt = 0; kt < nk; ++kt) {
;     const int buf = kt & 1;
;     const char* cA = smem + buf * STAGE + (wm * 32 * MI + r16) * 128;
;     const char* cB = smem + buf * STAGE + 32768 + (wn * 64 + r16) * 128;
; #pragma unroll
;     for (int k2 = 0; k2 < 2; ++k2) {
;       if (k2 == 1 && kt + 1 < nk) STAGE_TILE(buf ^ 1, (kt + 1) * 64)
;       const int po = ((4 * k2 + q4) ^ swz) * 16;
;       bf16x8 bf[4];
; #pragma unroll
;       for (int nt = 0; nt < 4; ++nt) bf[nt] = *(const bf16x8*)(cB + nt * 16 * 128 + po);
;       bf16x8 afc = *(const bf16x8*)(cA + po);
; #pragma unroll
;       for (int a = 0; a < MT; ++a) {
;         bf16x8 afn = afc;
;         if (a + 1 < MT) afn = *(const bf16x8*)(cA + (a + 1) * 16 * 128 + po);
;         __builtin_amdgcn_sched_barrier(0);
; #pragma unroll
;         for (int nt = 0; nt < 4; ++nt) acc[a][nt] = MFMA16(bf[nt], afc, acc[a][nt]);
;         __builtin_amdgcn_sched_barrier(0);
;         afc = afn;
;       }
;     }
;     asm volatile("s_waitcnt vmcnt(0)" ::: "memory");
;     __syncthreads();
;   }
	s_cbranch_scc1 .LBB0_75
	s_add_i32 s16, 0, 0x10000
	v_add_u32_e32 v138, s16, v148
	v_readlane_b32 s16, v254, 18
	s_nop 1
	v_add_u32_e32 v139, s16, v147
	v_add_u32_e32 v145, v139, v146
	ds_read_b128 v[130:133], v145
	ds_read_b128 v[134:137], v145 offset:2048
	ds_read_b128 v[148:151], v145 offset:4096
	ds_read_b128 v[152:155], v145 offset:6144
	v_add_u32_e32 v145, v138, v146
	ds_read_b128 v[156:159], v145
	ds_read_b128 v[160:163], v145 offset:2048
	s_waitcnt lgkmcnt(1)
	v_mfma_f32_16x16x32_bf16 v[126:129], v[130:133], v[156:159], v[126:129]
	v_mfma_f32_16x16x32_bf16 v[122:125], v[134:137], v[156:159], v[122:125]
	v_mfma_f32_16x16x32_bf16 v[118:121], v[148:151], v[156:159], v[118:121]
	v_mfma_f32_16x16x32_bf16 v[114:117], v[152:155], v[156:159], v[114:117]
	ds_read_b128 v[156:159], v145 offset:4096
	s_waitcnt lgkmcnt(1)
	v_mfma_f32_16x16x32_bf16 v[110:113], v[130:133], v[160:163], v[110:113]
	v_mfma_f32_16x16x32_bf16 v[106:109], v[134:137], v[160:163], v[106:109]
	v_mfma_f32_16x16x32_bf16 v[102:105], v[148:151], v[160:163], v[102:105]
	v_mfma_f32_16x16x32_bf16 v[98:101], v[152:155], v[160:163], v[98:101]
	ds_read_b128 v[160:163], v145 offset:6144
	s_waitcnt lgkmcnt(1)
	v_mfma_f32_16x16x32_bf16 v[94:97], v[130:133], v[156:159], v[94:97]
	v_mfma_f32_16x16x32_bf16 v[90:93], v[134:137], v[156:159], v[90:93]
	v_mfma_f32_16x16x32_bf16 v[86:89], v[148:151], v[156:159], v[86:89]
	v_mfma_f32_16x16x32_bf16 v[82:85], v[152:155], v[156:159], v[82:85]
	ds_read_b128 v[156:159], v145 offset:8192
	s_waitcnt lgkmcnt(1)
	v_mfma_f32_16x16x32_bf16 v[78:81], v[130:133], v[160:163], v[78:81]
	v_mfma_f32_16x16x32_bf16 v[74:77], v[134:137], v[160:163], v[74:77]
	v_mfma_f32_16x16x32_bf16 v[70:73], v[148:151], v[160:163], v[70:73]
	v_mfma_f32_16x16x32_bf16 v[66:69], v[152:155], v[160:163], v[66:69]
	ds_read_b128 v[160:163], v145 offset:10240
	s_waitcnt lgkmcnt(1)
	v_mfma_f32_16x16x32_bf16 v[62:65], v[130:133], v[156:159], v[62:65]
	v_mfma_f32_16x16x32_bf16 v[58:61], v[134:137], v[156:159], v[58:61]
	v_mfma_f32_16x16x32_bf16 v[54:57], v[148:151], v[156:159], v[54:57]
	v_mfma_f32_16x16x32_bf16 v[50:53], v[152:155], v[156:159], v[50:53]
	ds_read_b128 v[156:159], v145 offset:12288
	s_waitcnt lgkmcnt(1)
	v_mfma_f32_16x16x32_bf16 v[46:49], v[130:133], v[160:163], v[46:49]
	v_mfma_f32_16x16x32_bf16 v[42:45], v[134:137], v[160:163], v[42:45]
	v_mfma_f32_16x16x32_bf16 v[38:41], v[148:151], v[160:163], v[38:41]
	v_mfma_f32_16x16x32_bf16 v[34:37], v[152:155], v[160:163], v[34:37]
	ds_read_b128 v[160:163], v145 offset:14336
	s_waitcnt lgkmcnt(1)
	v_mfma_f32_16x16x32_bf16 v[30:33], v[130:133], v[156:159], v[30:33]
	v_mfma_f32_16x16x32_bf16 v[26:29], v[134:137], v[156:159], v[26:29]
	v_mfma_f32_16x16x32_bf16 v[22:25], v[148:151], v[156:159], v[22:25]
	v_mfma_f32_16x16x32_bf16 v[18:21], v[152:155], v[156:159], v[18:21]
	s_waitcnt lgkmcnt(0)
	v_mfma_f32_16x16x32_bf16 v[14:17], v[130:133], v[160:163], v[14:17]
	v_mfma_f32_16x16x32_bf16 v[10:13], v[134:137], v[160:163], v[10:13]
	v_mfma_f32_16x16x32_bf16 v[6:9], v[148:151], v[160:163], v[6:9]
	v_mfma_f32_16x16x32_bf16 v[2:5], v[152:155], v[160:163], v[2:5]
	v_add_u32_e32 v139, v139, v144
	ds_read_b128 v[130:133], v139
	ds_read_b128 v[134:137], v139 offset:2048
	ds_read_b128 v[146:149], v139 offset:4096
	ds_read_b128 v[150:153], v139 offset:6144
	v_add_u32_e32 v138, v138, v144
	ds_read_b128 v[154:157], v138
	ds_read_b128 v[158:161], v138 offset:2048
	s_waitcnt lgkmcnt(1)
	v_mfma_f32_16x16x32_bf16 v[126:129], v[130:133], v[154:157], v[126:129]
	v_mfma_f32_16x16x32_bf16 v[122:125], v[134:137], v[154:157], v[122:125]
	v_mfma_f32_16x16x32_bf16 v[118:121], v[146:149], v[154:157], v[118:121]
	v_mfma_f32_16x16x32_bf16 v[114:117], v[150:153], v[154:157], v[114:117]
	ds_read_b128 v[154:157], v138 offset:4096
	s_waitcnt lgkmcnt(1)
	v_mfma_f32_16x16x32_bf16 v[162:165], v[130:133], v[158:161], v[110:113]
	v_mfma_f32_16x16x32_bf16 v[166:169], v[134:137], v[158:161], v[106:109]
	v_mfma_f32_16x16x32_bf16 v[102:105], v[146:149], v[158:161], v[102:105]
	v_mfma_f32_16x16x32_bf16 v[98:101], v[150:153], v[158:161], v[98:101]
	s_nop 0
	ds_read_b128 v[106:109], v138 offset:6144
	s_waitcnt lgkmcnt(1)
	v_mfma_f32_16x16x32_bf16 v[94:97], v[130:133], v[154:157], v[94:97]
	v_mfma_f32_16x16x32_bf16 v[90:93], v[134:137], v[154:157], v[90:93]
	v_mfma_f32_16x16x32_bf16 v[86:89], v[146:149], v[154:157], v[86:89]
	v_mfma_f32_16x16x32_bf16 v[82:85], v[150:153], v[154:157], v[82:85]
	ds_read_b128 v[110:113], v138 offset:8192
	s_waitcnt lgkmcnt(1)
	v_mfma_f32_16x16x32_bf16 v[78:81], v[130:133], v[106:109], v[78:81]
	v_mfma_f32_16x16x32_bf16 v[74:77], v[134:137], v[106:109], v[74:77]
	v_mfma_f32_16x16x32_bf16 v[70:73], v[146:149], v[106:109], v[70:73]
	v_mfma_f32_16x16x32_bf16 v[66:69], v[150:153], v[106:109], v[66:69]
	ds_read_b128 v[106:109], v138 offset:10240
	s_waitcnt lgkmcnt(1)
	v_mfma_f32_16x16x32_bf16 v[62:65], v[130:133], v[110:113], v[62:65]
	v_mfma_f32_16x16x32_bf16 v[58:61], v[134:137], v[110:113], v[58:61]
	v_mfma_f32_16x16x32_bf16 v[54:57], v[146:149], v[110:113], v[54:57]
	v_mfma_f32_16x16x32_bf16 v[50:53], v[150:153], v[110:113], v[50:53]
	ds_read_b128 v[110:113], v138 offset:12288
	s_waitcnt lgkmcnt(1)
	v_mfma_f32_16x16x32_bf16 v[46:49], v[130:133], v[106:109], v[46:49]
	v_mfma_f32_16x16x32_bf16 v[42:45], v[134:137], v[106:109], v[42:45]
	v_mfma_f32_16x16x32_bf16 v[38:41], v[146:149], v[106:109], v[38:41]
	v_mfma_f32_16x16x32_bf16 v[34:37], v[150:153], v[106:109], v[34:37]
	ds_read_b128 v[106:109], v138 offset:14336
	s_waitcnt lgkmcnt(1)
; DI unsigned pack2(float a, float b) { hwf2_t f = {a, b}; return __builtin_bit_cast(unsigned, __builtin_convertvector(f, hwbf2_t)); }
; DI float fsigmoid(float x) { return __builtin_amdgcn_rcpf(1.f + __expf(-x)); }
; DI void phase_ffn_up(char* smem, const Params& p, int layer) {
;     ...
;   auto ep = [=](int row, int cb, int q4, const f32x4& c0, const f32x4& c1, const f32x4& c2, const f32x4& c3) {
;     const uint4 o = make_uint4(pack2(c0[0] * fsigmoid(c0[0]) * c0[1], c0[2] * fsigmoid(c0[2]) * c0[3]),
;                                pack2(c1[0] * fsigmoid(c1[0]) * c1[1], c1[2] * fsigmoid(c1[2]) * c1[3]),
;                                pack2(c2[0] * fsigmoid(c2[0]) * c2[1], c2[2] * fsigmoid(c2[2]) * c2[3]),
;                                pack2(c3[0] * fsigmoid(c3[0]) * c3[1], c3[2] * fsigmoid(c3[2]) * c3[3]));
;     *(uint4*)(Hh + (size_t)row * FH + (cb >> 1) + q4 * 8) = o;
	v_mfma_f32_16x16x32_bf16 v[30:33], v[130:133], v[110:113], v[30:33]
	v_mfma_f32_16x16x32_bf16 v[26:29], v[134:137], v[110:113], v[26:29]
	v_mfma_f32_16x16x32_bf16 v[22:25], v[146:149], v[110:113], v[22:25]
	v_mfma_f32_16x16x32_bf16 v[18:21], v[150:153], v[110:113], v[18:21]
	s_waitcnt lgkmcnt(0)
	v_mfma_f32_16x16x32_bf16 v[14:17], v[130:133], v[106:109], v[14:17]
	v_mfma_f32_16x16x32_bf16 v[10:13], v[134:137], v[106:109], v[10:13]
	v_mfma_f32_16x16x32_bf16 v[6:9], v[146:149], v[106:109], v[6:9]
	v_mfma_f32_16x16x32_bf16 v[2:5], v[150:153], v[106:109], v[2:5]
	v_or_b32_e32 v107, s38, v142
	v_lshl_add_u32 v110, v141, 7, v107
	v_mul_f32_e32 v107, 0xbfb8aa3b, v126
	v_mul_f32_e32 v108, 0xbfb8aa3b, v128
	v_exp_f32_e32 v107, v107
	v_exp_f32_e32 v109, v108
	v_lshl_or_b32 v106, v143, 6, s39
	v_ashrrev_i32_e32 v108, 1, v106
	v_add_f32_e32 v106, 1.0, v107
	v_add_f32_e32 v107, 1.0, v109
	v_rcp_f32_e32 v106, v106
	v_rcp_f32_e32 v107, v107
	v_mov_b32_e32 v112, v126
	v_mov_b32_e32 v113, v128
	v_mul_f32_e32 v111, 0xbfb8aa3b, v122
	v_pk_mul_f32 v[106:107], v[112:113], v[106:107]
	v_exp_f32_e32 v111, v111
	v_mul_f32_e32 v112, 0xbfb8aa3b, v124
	v_exp_f32_e32 v113, v112
	v_mov_b32_e32 v128, v127
	v_add_f32_e32 v111, 1.0, v111
	v_rcp_f32_e32 v112, v111
	v_add_f32_e32 v111, 1.0, v113
	v_rcp_f32_e32 v113, v111
	v_pk_mul_f32 v[106:107], v[128:129], v[106:107]
	v_mul_f32_e32 v111, 0xbfb8aa3b, v118
	v_cvt_pk_bf16_f32 v126, v106, v107
	v_mov_b32_e32 v106, v122
	v_mov_b32_e32 v107, v124
	v_pk_mul_f32 v[106:107], v[106:107], v[112:113]
	v_exp_f32_e32 v111, v111
	v_mul_f32_e32 v112, 0xbfb8aa3b, v120
	v_exp_f32_e32 v113, v112
	v_mov_b32_e32 v124, v123
	v_add_f32_e32 v111, 1.0, v111
	v_rcp_f32_e32 v112, v111
	v_add_f32_e32 v111, 1.0, v113
	v_rcp_f32_e32 v113, v111
	v_pk_mul_f32 v[106:107], v[124:125], v[106:107]
	v_mul_f32_e32 v111, 0xbfb8aa3b, v114
	v_cvt_pk_bf16_f32 v127, v106, v107
	v_mov_b32_e32 v106, v118
	v_mov_b32_e32 v107, v120
	v_pk_mul_f32 v[106:107], v[106:107], v[112:113]
	v_exp_f32_e32 v111, v111
	v_mul_f32_e32 v112, 0xbfb8aa3b, v116
	v_exp_f32_e32 v113, v112
	v_mov_b32_e32 v120, v119
	v_add_f32_e32 v111, 1.0, v111
	v_rcp_f32_e32 v112, v111
	v_add_f32_e32 v111, 1.0, v113
	v_rcp_f32_e32 v113, v111
	v_pk_mul_f32 v[106:107], v[120:121], v[106:107]
	v_readlane_b32 s52, v253, 40
	v_cvt_pk_bf16_f32 v128, v106, v107
	v_mov_b32_e32 v106, v114
	v_mov_b32_e32 v107, v116
	v_pk_mul_f32 v[106:107], v[106:107], v[112:113]
	v_mov_b32_e32 v116, v115
	v_mul_f32_e32 v111, 0xbfb8aa3b, v162
	v_pk_mul_f32 v[106:107], v[116:117], v[106:107]
	v_readlane_b32 s54, v253, 42
	v_readlane_b32 s55, v253, 43
	v_exp_f32_e32 v111, v111
	v_mul_f32_e32 v114, 0xbfb8aa3b, v164
	v_ashrrev_i32_e32 v109, 31, v108
	v_cvt_pk_bf16_f32 v129, v106, v107
	v_mov_b64_e32 v[106:107], s[54:55]
	s_movk_i32 s38, 0x1600
	v_exp_f32_e32 v114, v114
	v_mad_i64_i32 v[112:113], s[16:17], v110, s38, v[106:107]
	v_lshlrev_b64 v[108:109], 1, v[108:109]
	v_lshl_add_u64 v[112:113], v[112:113], 0, v[108:109]
	v_lshlrev_b32_e32 v190, 4, v140
	v_lshl_add_u64 v[112:113], v[112:113], 0, v[190:191]
	v_add_f32_e32 v111, 1.0, v111
	s_waitcnt vmcnt(0)
	s_barrier
	global_store_dwordx4 v[112:113], v[126:129], off
	v_rcp_f32_e32 v112, v111
	v_add_f32_e32 v111, 1.0, v114
	v_rcp_f32_e32 v113, v111
	v_mov_b32_e32 v114, v162
	v_mov_b32_e32 v115, v164
	v_mov_b32_e32 v164, v163
	v_pk_mul_f32 v[112:113], v[114:115], v[112:113]
	v_mul_f32_e32 v114, 0xbfb8aa3b, v166
	v_mul_f32_e32 v115, 0xbfb8aa3b, v168
	v_exp_f32_e32 v114, v114
	v_exp_f32_e32 v115, v115
	v_pk_mul_f32 v[112:113], v[164:165], v[112:113]
	v_mov_b32_e32 v116, v166
	v_add_f32_e32 v114, 1.0, v114
	v_add_f32_e32 v115, 1.0, v115
	v_rcp_f32_e32 v114, v114
	v_rcp_f32_e32 v115, v115
	v_cvt_pk_bf16_f32 v112, v112, v113
	v_mov_b32_e32 v117, v168
	v_mul_f32_e32 v113, 0xbfb8aa3b, v102
	v_pk_mul_f32 v[114:115], v[116:117], v[114:115]
	v_exp_f32_e32 v113, v113
	v_mul_f32_e32 v116, 0xbfb8aa3b, v104
	v_exp_f32_e32 v117, v116
	v_mov_b32_e32 v168, v167
	v_add_f32_e32 v113, 1.0, v113
	v_rcp_f32_e32 v116, v113
	v_add_f32_e32 v113, 1.0, v117
	v_rcp_f32_e32 v117, v113
	v_pk_mul_f32 v[114:115], v[168:169], v[114:115]
	v_or_b32_e32 v111, 16, v110
	v_cvt_pk_bf16_f32 v113, v114, v115
	v_mov_b32_e32 v114, v102
	v_mov_b32_e32 v115, v104
	v_mul_f32_e32 v102, 0xbfb8aa3b, v98
	v_pk_mul_f32 v[114:115], v[114:115], v[116:117]
	v_exp_f32_e32 v116, v102
	v_mul_f32_e32 v102, 0xbfb8aa3b, v100
	v_exp_f32_e32 v117, v102
	v_mov_b32_e32 v104, v103
	v_pk_mul_f32 v[102:103], v[104:105], v[114:115]
	v_add_f32_e32 v104, 1.0, v116
	v_add_f32_e32 v105, 1.0, v117
	v_rcp_f32_e32 v104, v104
	v_rcp_f32_e32 v105, v105
	v_cvt_pk_bf16_f32 v114, v102, v103
	v_mov_b32_e32 v102, v98
	v_mov_b32_e32 v103, v100
	v_pk_mul_f32 v[102:103], v[102:103], v[104:105]
	v_mov_b32_e32 v100, v99
	v_pk_mul_f32 v[98:99], v[100:101], v[102:103]
	v_mul_f32_e32 v100, 0xbfb8aa3b, v94
	v_mul_f32_e32 v101, 0xbfb8aa3b, v96
	v_exp_f32_e32 v100, v100
	v_exp_f32_e32 v101, v101
	v_cvt_pk_bf16_f32 v115, v98, v99
	v_mad_i64_i32 v[98:99], s[16:17], v111, s38, v[106:107]
	v_lshl_add_u64 v[98:99], v[98:99], 0, v[108:109]
	v_lshl_add_u64 v[98:99], v[98:99], 0, v[190:191]
	global_store_dwordx4 v[98:99], v[112:115], off
	v_add_f32_e32 v98, 1.0, v100
	v_add_f32_e32 v99, 1.0, v101
	v_rcp_f32_e32 v98, v98
	v_rcp_f32_e32 v99, v99
	v_mov_b32_e32 v100, v94
	v_mov_b32_e32 v101, v96
	v_mul_f32_e32 v94, 0xbfb8aa3b, v90
	v_pk_mul_f32 v[98:99], v[100:101], v[98:99]
	v_exp_f32_e32 v100, v94
	v_mul_f32_e32 v94, 0xbfb8aa3b, v92
	v_exp_f32_e32 v101, v94
	v_mov_b32_e32 v96, v95
	v_pk_mul_f32 v[94:95], v[96:97], v[98:99]
	v_add_f32_e32 v96, 1.0, v100
	v_add_f32_e32 v97, 1.0, v101
; DI unsigned pack2(float a, float b) { hwf2_t f = {a, b}; return __builtin_bit_cast(unsigned, __builtin_convertvector(f, hwbf2_t)); }
; DI float fsigmoid(float x) { return __builtin_amdgcn_rcpf(1.f + __expf(-x)); }
; DI void phase_ffn_up(char* smem, const Params& p, int layer) {
;     ...
;   auto ep = [=](int row, int cb, int q4, const f32x4& c0, const f32x4& c1, const f32x4& c2, const f32x4& c3) {
;     const uint4 o = make_uint4(pack2(c0[0] * fsigmoid(c0[0]) * c0[1], c0[2] * fsigmoid(c0[2]) * c0[3]),
;                                pack2(c1[0] * fsigmoid(c1[0]) * c1[1], c1[2] * fsigmoid(c1[2]) * c1[3]),
;                                pack2(c2[0] * fsigmoid(c2[0]) * c2[1], c2[2] * fsigmoid(c2[2]) * c2[3]),
;                                pack2(c3[0] * fsigmoid(c3[0]) * c3[1], c3[2] * fsigmoid(c3[2]) * c3[3]));
;     *(uint4*)(Hh + (size_t)row * FH + (cb >> 1) + q4 * 8) = o;
	v_rcp_f32_e32 v96, v96
	v_rcp_f32_e32 v97, v97
	v_mov_b32_e32 v98, v90
	v_mul_f32_e32 v90, 0xbfb8aa3b, v86
	v_cvt_pk_bf16_f32 v94, v94, v95
	v_mov_b32_e32 v99, v92
	v_exp_f32_e32 v95, v90
	v_mul_f32_e32 v90, 0xbfb8aa3b, v88
	v_pk_mul_f32 v[96:97], v[98:99], v[96:97]
	v_exp_f32_e32 v98, v90
	v_mov_b32_e32 v92, v91
	v_pk_mul_f32 v[90:91], v[92:93], v[96:97]
	v_add_f32_e32 v92, 1.0, v95
	v_add_f32_e32 v93, 1.0, v98
	v_rcp_f32_e32 v92, v92
	v_rcp_f32_e32 v93, v93
	v_cvt_pk_bf16_f32 v95, v90, v91
	v_mov_b32_e32 v90, v86
	v_mov_b32_e32 v91, v88
	v_mul_f32_e32 v86, 0xbfb8aa3b, v82
	v_pk_mul_f32 v[90:91], v[90:91], v[92:93]
	v_exp_f32_e32 v92, v86
	v_mul_f32_e32 v86, 0xbfb8aa3b, v84
	v_exp_f32_e32 v93, v86
	v_mov_b32_e32 v88, v87
	v_pk_mul_f32 v[86:87], v[88:89], v[90:91]
	v_add_f32_e32 v88, 1.0, v92
	v_add_f32_e32 v89, 1.0, v93
	v_rcp_f32_e32 v88, v88
	v_rcp_f32_e32 v89, v89
	v_cvt_pk_bf16_f32 v96, v86, v87
	v_mov_b32_e32 v86, v82
	v_mov_b32_e32 v87, v84
	v_pk_mul_f32 v[86:87], v[86:87], v[88:89]
	v_mov_b32_e32 v84, v83
	v_pk_mul_f32 v[82:83], v[84:85], v[86:87]
	v_mul_f32_e32 v84, 0xbfb8aa3b, v78
	v_mul_f32_e32 v85, 0xbfb8aa3b, v80
	v_or_b32_e32 v102, 32, v110
	v_exp_f32_e32 v84, v84
	v_exp_f32_e32 v85, v85
	v_cvt_pk_bf16_f32 v97, v82, v83
	v_mad_i64_i32 v[82:83], s[16:17], v102, s38, v[106:107]
	v_lshl_add_u64 v[82:83], v[82:83], 0, v[108:109]
	v_lshl_add_u64 v[82:83], v[82:83], 0, v[190:191]
	global_store_dwordx4 v[82:83], v[94:97], off
	v_add_f32_e32 v82, 1.0, v84
	v_add_f32_e32 v83, 1.0, v85
	v_rcp_f32_e32 v82, v82
	v_rcp_f32_e32 v83, v83
	v_mov_b32_e32 v84, v78
	v_mov_b32_e32 v85, v80
	v_mul_f32_e32 v78, 0xbfb8aa3b, v74
	v_pk_mul_f32 v[82:83], v[84:85], v[82:83]
	v_exp_f32_e32 v84, v78
	v_mul_f32_e32 v78, 0xbfb8aa3b, v76
	v_exp_f32_e32 v85, v78
	v_mov_b32_e32 v80, v79
	v_pk_mul_f32 v[78:79], v[80:81], v[82:83]
	v_add_f32_e32 v80, 1.0, v84
	v_add_f32_e32 v81, 1.0, v85
	v_rcp_f32_e32 v80, v80
	v_rcp_f32_e32 v81, v81
	v_mov_b32_e32 v82, v74
	v_mul_f32_e32 v74, 0xbfb8aa3b, v70
	v_cvt_pk_bf16_f32 v78, v78, v79
	v_mov_b32_e32 v83, v76
	v_exp_f32_e32 v79, v74
	v_mul_f32_e32 v74, 0xbfb8aa3b, v72
	v_pk_mul_f32 v[80:81], v[82:83], v[80:81]
	v_exp_f32_e32 v82, v74
	v_mov_b32_e32 v76, v75
	v_pk_mul_f32 v[74:75], v[76:77], v[80:81]
	v_add_f32_e32 v76, 1.0, v79
	v_add_f32_e32 v77, 1.0, v82
	v_rcp_f32_e32 v76, v76
	v_rcp_f32_e32 v77, v77
	v_cvt_pk_bf16_f32 v79, v74, v75
	v_mov_b32_e32 v74, v70
	v_mov_b32_e32 v75, v72
	v_mul_f32_e32 v70, 0xbfb8aa3b, v66
	v_pk_mul_f32 v[74:75], v[74:75], v[76:77]
	v_exp_f32_e32 v76, v70
	v_mul_f32_e32 v70, 0xbfb8aa3b, v68
	v_exp_f32_e32 v77, v70
	v_mov_b32_e32 v72, v71
	v_pk_mul_f32 v[70:71], v[72:73], v[74:75]
	v_add_f32_e32 v72, 1.0, v76
	v_add_f32_e32 v73, 1.0, v77
	v_rcp_f32_e32 v72, v72
	v_rcp_f32_e32 v73, v73
	v_cvt_pk_bf16_f32 v80, v70, v71
	v_mov_b32_e32 v70, v66
	v_mov_b32_e32 v71, v68
	v_pk_mul_f32 v[70:71], v[70:71], v[72:73]
	v_mov_b32_e32 v68, v67
	v_pk_mul_f32 v[66:67], v[68:69], v[70:71]
	v_mul_f32_e32 v68, 0xbfb8aa3b, v62
	v_mul_f32_e32 v69, 0xbfb8aa3b, v64
	v_or_b32_e32 v86, 48, v110
	v_exp_f32_e32 v68, v68
	v_exp_f32_e32 v69, v69
	v_cvt_pk_bf16_f32 v81, v66, v67
	v_mad_i64_i32 v[66:67], s[16:17], v86, s38, v[106:107]
	v_lshl_add_u64 v[66:67], v[66:67], 0, v[108:109]
	v_lshl_add_u64 v[66:67], v[66:67], 0, v[190:191]
	global_store_dwordx4 v[66:67], v[78:81], off
	v_add_f32_e32 v66, 1.0, v68
	v_add_f32_e32 v67, 1.0, v69
	v_rcp_f32_e32 v66, v66
	v_rcp_f32_e32 v67, v67
	v_mov_b32_e32 v68, v62
	v_mov_b32_e32 v69, v64
	v_mul_f32_e32 v62, 0xbfb8aa3b, v58
	v_pk_mul_f32 v[66:67], v[68:69], v[66:67]
	v_exp_f32_e32 v68, v62
	v_mul_f32_e32 v62, 0xbfb8aa3b, v60
	v_exp_f32_e32 v69, v62
	v_mov_b32_e32 v64, v63
	v_pk_mul_f32 v[62:63], v[64:65], v[66:67]
	v_add_f32_e32 v64, 1.0, v68
	v_add_f32_e32 v65, 1.0, v69
	v_rcp_f32_e32 v64, v64
	v_rcp_f32_e32 v65, v65
	v_mov_b32_e32 v66, v58
	v_mul_f32_e32 v58, 0xbfb8aa3b, v54
	v_cvt_pk_bf16_f32 v62, v62, v63
	v_mov_b32_e32 v67, v60
	v_exp_f32_e32 v63, v58
	v_mul_f32_e32 v58, 0xbfb8aa3b, v56
	v_pk_mul_f32 v[64:65], v[66:67], v[64:65]
	v_exp_f32_e32 v66, v58
	v_mov_b32_e32 v60, v59
	v_pk_mul_f32 v[58:59], v[60:61], v[64:65]
	v_add_f32_e32 v60, 1.0, v63
	v_add_f32_e32 v61, 1.0, v66
	v_rcp_f32_e32 v60, v60
	v_rcp_f32_e32 v61, v61
	v_cvt_pk_bf16_f32 v63, v58, v59
	v_mov_b32_e32 v58, v54
	v_mov_b32_e32 v59, v56
	v_mul_f32_e32 v54, 0xbfb8aa3b, v50
	v_pk_mul_f32 v[58:59], v[58:59], v[60:61]
	v_exp_f32_e32 v60, v54
	v_mul_f32_e32 v54, 0xbfb8aa3b, v52
	v_exp_f32_e32 v61, v54
	v_mov_b32_e32 v56, v55
	v_pk_mul_f32 v[54:55], v[56:57], v[58:59]
	v_add_f32_e32 v56, 1.0, v60
	v_add_f32_e32 v57, 1.0, v61
	v_rcp_f32_e32 v56, v56
	v_rcp_f32_e32 v57, v57
	v_cvt_pk_bf16_f32 v64, v54, v55
	v_mov_b32_e32 v54, v50
	v_mov_b32_e32 v55, v52
	v_pk_mul_f32 v[54:55], v[54:55], v[56:57]
	v_mov_b32_e32 v52, v51
	v_pk_mul_f32 v[50:51], v[52:53], v[54:55]
	v_mul_f32_e32 v52, 0xbfb8aa3b, v46
	v_mul_f32_e32 v53, 0xbfb8aa3b, v48
	v_or_b32_e32 v70, 64, v110
	v_exp_f32_e32 v52, v52
	v_exp_f32_e32 v53, v53
	v_cvt_pk_bf16_f32 v65, v50, v51
	v_mad_i64_i32 v[50:51], s[16:17], v70, s38, v[106:107]
	v_lshl_add_u64 v[50:51], v[50:51], 0, v[108:109]
	v_lshl_add_u64 v[50:51], v[50:51], 0, v[190:191]
	global_store_dwordx4 v[50:51], v[62:65], off
	v_add_f32_e32 v50, 1.0, v52
	v_add_f32_e32 v51, 1.0, v53
	v_rcp_f32_e32 v50, v50
	v_rcp_f32_e32 v51, v51
	v_mov_b32_e32 v52, v46
	v_mov_b32_e32 v53, v48
	v_mul_f32_e32 v46, 0xbfb8aa3b, v42
	v_pk_mul_f32 v[50:51], v[52:53], v[50:51]
	v_exp_f32_e32 v52, v46
	v_mul_f32_e32 v46, 0xbfb8aa3b, v44
	v_exp_f32_e32 v53, v46
	v_mov_b32_e32 v48, v47
	v_pk_mul_f32 v[46:47], v[48:49], v[50:51]
; DI unsigned pack2(float a, float b) { hwf2_t f = {a, b}; return __builtin_bit_cast(unsigned, __builtin_convertvector(f, hwbf2_t)); }
; DI float fsigmoid(float x) { return __builtin_amdgcn_rcpf(1.f + __expf(-x)); }
; template <int TMI, class F>
; DI void for_tiles_xcd(int MT, int NT, const F& f) {
;     ...
;     for (int c = x; c * 32 < total_full; c += 8)
;       for (int kk = slot; kk < 32; kk += nslots) {
;         const int L = c * 32 + kk;
;         if (L >= total_full) break;
;         int mt, nt; decode(L, mt, nt);
;         f(mt * 256, nt, std::integral_constant<int, 4>{});
; DI void phase_ffn_up(char* smem, const Params& p, int layer) {
;     ...
;   auto ep = [=](int row, int cb, int q4, const f32x4& c0, const f32x4& c1, const f32x4& c2, const f32x4& c3) {
;     const uint4 o = make_uint4(pack2(c0[0] * fsigmoid(c0[0]) * c0[1], c0[2] * fsigmoid(c0[2]) * c0[3]),
;                                pack2(c1[0] * fsigmoid(c1[0]) * c1[1], c1[2] * fsigmoid(c1[2]) * c1[3]),
;                                pack2(c2[0] * fsigmoid(c2[0]) * c2[1], c2[2] * fsigmoid(c2[2]) * c2[3]),
;                                pack2(c3[0] * fsigmoid(c3[0]) * c3[1], c3[2] * fsigmoid(c3[2]) * c3[3]));
;     *(uint4*)(Hh + (size_t)row * FH + (cb >> 1) + q4 * 8) = o;
	v_add_f32_e32 v48, 1.0, v52
	v_add_f32_e32 v49, 1.0, v53
	v_rcp_f32_e32 v48, v48
	v_rcp_f32_e32 v49, v49
	v_mov_b32_e32 v50, v42
	v_mul_f32_e32 v42, 0xbfb8aa3b, v38
	v_cvt_pk_bf16_f32 v46, v46, v47
	v_mov_b32_e32 v51, v44
	v_exp_f32_e32 v47, v42
	v_mul_f32_e32 v42, 0xbfb8aa3b, v40
	v_pk_mul_f32 v[48:49], v[50:51], v[48:49]
	v_exp_f32_e32 v50, v42
	v_mov_b32_e32 v44, v43
	v_pk_mul_f32 v[42:43], v[44:45], v[48:49]
	v_add_f32_e32 v44, 1.0, v47
	v_add_f32_e32 v45, 1.0, v50
	v_rcp_f32_e32 v44, v44
	v_rcp_f32_e32 v45, v45
	v_cvt_pk_bf16_f32 v47, v42, v43
	v_mov_b32_e32 v42, v38
	v_mov_b32_e32 v43, v40
	v_mul_f32_e32 v38, 0xbfb8aa3b, v34
	v_pk_mul_f32 v[42:43], v[42:43], v[44:45]
	v_exp_f32_e32 v44, v38
	v_mul_f32_e32 v38, 0xbfb8aa3b, v36
	v_exp_f32_e32 v45, v38
	v_mov_b32_e32 v40, v39
	v_pk_mul_f32 v[38:39], v[40:41], v[42:43]
	v_add_f32_e32 v40, 1.0, v44
	v_add_f32_e32 v41, 1.0, v45
	v_rcp_f32_e32 v40, v40
	v_rcp_f32_e32 v41, v41
	v_cvt_pk_bf16_f32 v48, v38, v39
	v_mov_b32_e32 v38, v34
	v_mov_b32_e32 v39, v36
	v_pk_mul_f32 v[38:39], v[38:39], v[40:41]
	v_mov_b32_e32 v36, v35
	v_pk_mul_f32 v[34:35], v[36:37], v[38:39]
	v_mul_f32_e32 v36, 0xbfb8aa3b, v30
	v_mul_f32_e32 v37, 0xbfb8aa3b, v32
	v_or_b32_e32 v54, 0x50, v110
	v_exp_f32_e32 v36, v36
	v_exp_f32_e32 v37, v37
	v_cvt_pk_bf16_f32 v49, v34, v35
	v_mad_i64_i32 v[34:35], s[16:17], v54, s38, v[106:107]
	v_lshl_add_u64 v[34:35], v[34:35], 0, v[108:109]
	v_lshl_add_u64 v[34:35], v[34:35], 0, v[190:191]
	global_store_dwordx4 v[34:35], v[46:49], off
	v_add_f32_e32 v34, 1.0, v36
	v_add_f32_e32 v35, 1.0, v37
	v_rcp_f32_e32 v34, v34
	v_rcp_f32_e32 v35, v35
	v_mov_b32_e32 v36, v30
	v_mov_b32_e32 v37, v32
	v_mul_f32_e32 v30, 0xbfb8aa3b, v26
	v_pk_mul_f32 v[34:35], v[36:37], v[34:35]
	v_exp_f32_e32 v36, v30
	v_mul_f32_e32 v30, 0xbfb8aa3b, v28
	v_exp_f32_e32 v37, v30
	v_mov_b32_e32 v32, v31
	v_pk_mul_f32 v[30:31], v[32:33], v[34:35]
	v_add_f32_e32 v32, 1.0, v36
	v_add_f32_e32 v33, 1.0, v37
	v_rcp_f32_e32 v32, v32
	v_rcp_f32_e32 v33, v33
	v_mov_b32_e32 v34, v26
	v_mul_f32_e32 v26, 0xbfb8aa3b, v22
	v_cvt_pk_bf16_f32 v30, v30, v31
	v_mov_b32_e32 v35, v28
	v_exp_f32_e32 v31, v26
	v_mul_f32_e32 v26, 0xbfb8aa3b, v24
	v_pk_mul_f32 v[32:33], v[34:35], v[32:33]
	v_exp_f32_e32 v34, v26
	v_mov_b32_e32 v28, v27
	v_pk_mul_f32 v[26:27], v[28:29], v[32:33]
	v_add_f32_e32 v28, 1.0, v31
	v_add_f32_e32 v29, 1.0, v34
	v_rcp_f32_e32 v28, v28
	v_rcp_f32_e32 v29, v29
	v_cvt_pk_bf16_f32 v31, v26, v27
	v_mov_b32_e32 v26, v22
	v_mov_b32_e32 v27, v24
	v_mul_f32_e32 v22, 0xbfb8aa3b, v18
	v_pk_mul_f32 v[26:27], v[26:27], v[28:29]
	v_exp_f32_e32 v28, v22
	v_mul_f32_e32 v22, 0xbfb8aa3b, v20
	v_exp_f32_e32 v29, v22
	v_mov_b32_e32 v24, v23
	v_pk_mul_f32 v[22:23], v[24:25], v[26:27]
	v_add_f32_e32 v24, 1.0, v28
	v_add_f32_e32 v25, 1.0, v29
	v_rcp_f32_e32 v24, v24
	v_rcp_f32_e32 v25, v25
	v_cvt_pk_bf16_f32 v32, v22, v23
	v_mov_b32_e32 v22, v18
	v_mov_b32_e32 v23, v20
	v_pk_mul_f32 v[22:23], v[22:23], v[24:25]
	v_mov_b32_e32 v20, v19
	v_pk_mul_f32 v[18:19], v[20:21], v[22:23]
	v_mul_f32_e32 v20, 0xbfb8aa3b, v14
	v_mul_f32_e32 v21, 0xbfb8aa3b, v16
	v_or_b32_e32 v38, 0x60, v110
	v_exp_f32_e32 v20, v20
	v_exp_f32_e32 v21, v21
	v_cvt_pk_bf16_f32 v33, v18, v19
	v_mad_i64_i32 v[18:19], s[16:17], v38, s38, v[106:107]
	v_lshl_add_u64 v[18:19], v[18:19], 0, v[108:109]
	v_lshl_add_u64 v[18:19], v[18:19], 0, v[190:191]
	global_store_dwordx4 v[18:19], v[30:33], off
	v_add_f32_e32 v18, 1.0, v20
	v_add_f32_e32 v19, 1.0, v21
	v_rcp_f32_e32 v18, v18
	v_rcp_f32_e32 v19, v19
	v_mov_b32_e32 v20, v14
	v_mov_b32_e32 v21, v16
	v_mul_f32_e32 v14, 0xbfb8aa3b, v10
	v_pk_mul_f32 v[18:19], v[20:21], v[18:19]
	v_exp_f32_e32 v20, v14
	v_mul_f32_e32 v14, 0xbfb8aa3b, v12
	v_exp_f32_e32 v21, v14
	v_mov_b32_e32 v16, v15
	v_pk_mul_f32 v[14:15], v[16:17], v[18:19]
	v_add_f32_e32 v16, 1.0, v20
	v_add_f32_e32 v17, 1.0, v21
	v_rcp_f32_e32 v16, v16
	v_rcp_f32_e32 v17, v17
	v_mov_b32_e32 v18, v10
	v_mul_f32_e32 v10, 0xbfb8aa3b, v6
	v_cvt_pk_bf16_f32 v14, v14, v15
	v_mov_b32_e32 v19, v12
	v_exp_f32_e32 v15, v10
	v_mul_f32_e32 v10, 0xbfb8aa3b, v8
	v_pk_mul_f32 v[16:17], v[18:19], v[16:17]
	v_exp_f32_e32 v18, v10
	v_mov_b32_e32 v12, v11
	v_pk_mul_f32 v[10:11], v[12:13], v[16:17]
	v_add_f32_e32 v12, 1.0, v15
	v_add_f32_e32 v13, 1.0, v18
	v_rcp_f32_e32 v12, v12
	v_rcp_f32_e32 v13, v13
	v_cvt_pk_bf16_f32 v15, v10, v11
	v_mov_b32_e32 v10, v6
	v_mov_b32_e32 v11, v8
	v_mul_f32_e32 v6, 0xbfb8aa3b, v2
	v_pk_mul_f32 v[10:11], v[10:11], v[12:13]
	v_exp_f32_e32 v12, v6
	v_mul_f32_e32 v6, 0xbfb8aa3b, v4
	v_exp_f32_e32 v13, v6
	v_mov_b32_e32 v8, v7
	v_pk_mul_f32 v[6:7], v[8:9], v[10:11]
	v_add_f32_e32 v8, 1.0, v12
	v_add_f32_e32 v9, 1.0, v13
	v_rcp_f32_e32 v8, v8
	v_rcp_f32_e32 v9, v9
	v_cvt_pk_bf16_f32 v16, v6, v7
	v_mov_b32_e32 v6, v2
	v_mov_b32_e32 v7, v4
	v_pk_mul_f32 v[6:7], v[6:7], v[8:9]
	v_mov_b32_e32 v4, v3
	v_or_b32_e32 v22, 0x70, v110
	v_pk_mul_f32 v[2:3], v[4:5], v[6:7]
	s_add_i32 s37, s37, s30
	v_cvt_pk_bf16_f32 v17, v2, v3
	v_mad_i64_i32 v[2:3], s[16:17], v22, s38, v[106:107]
	v_lshl_add_u64 v[2:3], v[2:3], 0, v[108:109]
	s_cmp_gt_i32 s37, 31
	v_lshl_add_u64 v[2:3], v[2:3], 0, v[190:191]
	s_cselect_b64 s[16:17], -1, 0
	v_readlane_b32 s53, v253, 41
	v_readlane_b32 s56, v253, 44
	v_readlane_b32 s57, v253, 45
	v_readlane_b32 s58, v253, 46
	v_readlane_b32 s59, v253, 47
	v_readlane_b32 s60, v253, 48
	v_readlane_b32 s61, v253, 49
	v_readlane_b32 s62, v253, 50
	v_readlane_b32 s63, v253, 51
	v_readlane_b32 s64, v253, 52
	v_readlane_b32 s65, v253, 53
	v_readlane_b32 s66, v253, 54
	v_readlane_b32 s67, v253, 55
	global_store_dwordx4 v[2:3], v[14:17], off
	s_branch .LBB0_68

; #define MFMA16(a, b, c) __builtin_amdgcn_mfma_f32_16x16x32_bf16((a), (b), (c), 0, 0, 0)
;     ...
;   for (int kt = 0; kt < nk; ++kt) {
;     const int buf = kt & 1;
;     const char* cA = smem + buf * STAGE + (wm * 32 * MI + r16) * 128;
;     const char* cB = smem + buf * STAGE + 32768 + (wn * 64 + r16) * 128;
; #pragma unroll
;     for (int k2 = 0; k2 < 2; ++k2) {
;       if (k2 == 1 && kt + 1 < nk) STAGE_TILE(buf ^ 1, (kt + 1) * 64)
;       const int po = ((4 * k2 + q4) ^ swz) * 16;
;       bf16x8 bf[4];
; #pragma unroll
;       for (int nt = 0; nt < 4; ++nt) bf[nt] = *(const bf16x8*)(cB + nt * 16 * 128 + po);
;       bf16x8 afc = *(const bf16x8*)(cA + po);
; #pragma unroll
;       for (int a = 0; a < MT; ++a) {
;         bf16x8 afn = afc;
;         if (a + 1 < MT) afn = *(const bf16x8*)(cA + (a + 1) * 16 * 128 + po);
;         __builtin_amdgcn_sched_barrier(0);
; #pragma unroll
;         for (int nt = 0; nt < 4; ++nt) acc[a][nt] = MFMA16(bf[nt], afc, acc[a][nt]);
;         __builtin_amdgcn_sched_barrier(0);
;         afc = afn;
;       }
;     }
;     asm volatile("s_waitcnt vmcnt(0)" ::: "memory");
;     __syncthreads();
;   }
.LBB0_107:
	s_and_b32 s46, s45, 0x10000
	s_add_i32 s47, s46, 0
	s_xor_b32 s46, s46, 0x10000
	v_add_u32_e32 v174, s47, v147
	v_add_u32_e32 v162, v174, v146
	v_add_u32_e32 v149, s47, v148
	ds_read_b128 v[150:153], v162 offset:32768
	ds_read_b128 v[154:157], v162 offset:34816
	ds_read_b128 v[158:161], v162 offset:36864
	ds_read_b128 v[162:165], v162 offset:38912
	v_add_u32_e32 v175, v149, v146
	ds_read_b128 v[166:169], v175
	ds_read_b128 v[170:173], v175 offset:2048
	s_waitcnt lgkmcnt(1)
	v_mfma_f32_16x16x32_bf16 v[126:129], v[150:153], v[166:169], v[126:129]
	v_readfirstlane_b32 s47, v145
	v_mfma_f32_16x16x32_bf16 v[122:125], v[154:157], v[166:169], v[122:125]
	s_nop 0
	v_mfma_f32_16x16x32_bf16 v[118:121], v[158:161], v[166:169], v[118:121]
	s_add_u32 s47, s47, s46
	v_mfma_f32_16x16x32_bf16 v[114:117], v[162:165], v[166:169], v[114:117]
	ds_read_b128 v[166:169], v175 offset:4096
	s_add_u32 m0, s47, 0x0
	s_waitcnt lgkmcnt(1)
	v_mfma_f32_16x16x32_bf16 v[110:113], v[150:153], v[170:173], v[110:113]
	global_load_lds_dwordx4 v176, s[100:101]
	v_mfma_f32_16x16x32_bf16 v[106:109], v[154:157], v[170:173], v[106:109]
	s_add_u32 m0, s47, 0x2000
	v_mfma_f32_16x16x32_bf16 v[102:105], v[158:161], v[170:173], v[102:105]
	global_load_lds_dwordx4 v177, s[100:101]
	v_mfma_f32_16x16x32_bf16 v[98:101], v[162:165], v[170:173], v[98:101]
	ds_read_b128 v[170:173], v175 offset:6144
	s_add_u32 m0, s47, 0x4000
	s_waitcnt lgkmcnt(1)
	v_mfma_f32_16x16x32_bf16 v[94:97], v[150:153], v[166:169], v[94:97]
	global_load_lds_dwordx4 v178, s[100:101]
	v_mfma_f32_16x16x32_bf16 v[90:93], v[154:157], v[166:169], v[90:93]
	s_add_u32 m0, s47, 0x6000
	v_mfma_f32_16x16x32_bf16 v[86:89], v[158:161], v[166:169], v[86:89]
	global_load_lds_dwordx4 v179, s[100:101]
	v_mfma_f32_16x16x32_bf16 v[82:85], v[162:165], v[166:169], v[82:85]
	ds_read_b128 v[166:169], v175 offset:8192
	s_add_u32 m0, s47, 0x8000
	s_waitcnt lgkmcnt(1)
	v_mfma_f32_16x16x32_bf16 v[78:81], v[150:153], v[170:173], v[78:81]
	global_load_lds_dwordx4 v180, s[100:101]
	v_mfma_f32_16x16x32_bf16 v[74:77], v[154:157], v[170:173], v[74:77]
	s_add_u32 m0, s47, 0xa000
	v_mfma_f32_16x16x32_bf16 v[70:73], v[158:161], v[170:173], v[70:73]
	global_load_lds_dwordx4 v181, s[100:101]
	v_mfma_f32_16x16x32_bf16 v[66:69], v[162:165], v[170:173], v[66:69]
	ds_read_b128 v[170:173], v175 offset:10240
	s_add_u32 m0, s47, 0xc000
	s_waitcnt lgkmcnt(1)
	v_mfma_f32_16x16x32_bf16 v[62:65], v[150:153], v[166:169], v[62:65]
	global_load_lds_dwordx4 v182, s[100:101]
	v_mfma_f32_16x16x32_bf16 v[58:61], v[154:157], v[166:169], v[58:61]
	s_add_u32 m0, s47, 0xe000
	v_mfma_f32_16x16x32_bf16 v[54:57], v[158:161], v[166:169], v[54:57]
	global_load_lds_dwordx4 v183, s[100:101]
	v_mfma_f32_16x16x32_bf16 v[50:53], v[162:165], v[166:169], v[50:53]
	ds_read_b128 v[166:169], v175 offset:12288
	v_add_u32_e32 v203, v174, v144
	s_waitcnt lgkmcnt(1)
	v_mfma_f32_16x16x32_bf16 v[46:49], v[150:153], v[170:173], v[46:49]
	v_add_u32_e32 v192, v149, v144
	v_mfma_f32_16x16x32_bf16 v[42:45], v[154:157], v[170:173], v[42:45]
	ds_read_b128 v[204:207], v203 offset:32768
	v_mfma_f32_16x16x32_bf16 v[38:41], v[158:161], v[170:173], v[38:41]
	ds_read_b128 v[208:211], v203 offset:34816
	v_mfma_f32_16x16x32_bf16 v[34:37], v[162:165], v[170:173], v[34:37]
	ds_read_b128 v[170:173], v175 offset:14336
	ds_read_b128 v[212:215], v203 offset:36864
	s_waitcnt lgkmcnt(4)
	v_mfma_f32_16x16x32_bf16 v[30:33], v[150:153], v[166:169], v[30:33]
	ds_read_b128 v[216:219], v203 offset:38912
	v_mfma_f32_16x16x32_bf16 v[26:29], v[154:157], v[166:169], v[26:29]
	ds_read_b128 v[220:223], v192
	v_mfma_f32_16x16x32_bf16 v[22:25], v[158:161], v[166:169], v[22:25]
	ds_read_b128 v[198:201], v192 offset:2048
	v_mfma_f32_16x16x32_bf16 v[18:21], v[162:165], v[166:169], v[18:21]
	s_waitcnt lgkmcnt(4)
	v_mfma_f32_16x16x32_bf16 v[14:17], v[150:153], v[170:173], v[14:17]
	v_mfma_f32_16x16x32_bf16 v[10:13], v[154:157], v[170:173], v[10:13]
	v_mfma_f32_16x16x32_bf16 v[6:9], v[158:161], v[170:173], v[6:9]
	v_mfma_f32_16x16x32_bf16 v[2:5], v[162:165], v[170:173], v[2:5]
	s_waitcnt lgkmcnt(1)
	v_mfma_f32_16x16x32_bf16 v[126:129], v[204:207], v[220:223], v[126:129]
	s_add_u32 s100, s100, 0x80
	v_mfma_f32_16x16x32_bf16 v[122:125], v[208:211], v[220:223], v[122:125]
	s_addc_u32 s101, s101, 0
	v_mfma_f32_16x16x32_bf16 v[118:121], v[212:215], v[220:223], v[118:121]
	s_add_u32 s22, s22, 0x80
	v_mfma_f32_16x16x32_bf16 v[114:117], v[216:219], v[220:223], v[114:117]
	ds_read_b128 v[220:223], v192 offset:4096
	s_waitcnt lgkmcnt(1)
	v_mfma_f32_16x16x32_bf16 v[110:113], v[204:207], v[198:201], v[110:113]
	s_addc_u32 s23, s23, 0
	v_mfma_f32_16x16x32_bf16 v[106:109], v[208:211], v[198:201], v[106:109]
	s_add_i32 s45, s45, 0x10000
	v_mfma_f32_16x16x32_bf16 v[102:105], v[212:215], v[198:201], v[102:105]
	v_mfma_f32_16x16x32_bf16 v[98:101], v[216:219], v[198:201], v[98:101]
	ds_read_b128 v[198:201], v192 offset:6144
	s_waitcnt lgkmcnt(1)
	v_mfma_f32_16x16x32_bf16 v[94:97], v[204:207], v[220:223], v[94:97]
	v_mfma_f32_16x16x32_bf16 v[90:93], v[208:211], v[220:223], v[90:93]
	v_mfma_f32_16x16x32_bf16 v[86:89], v[212:215], v[220:223], v[86:89]
	v_mfma_f32_16x16x32_bf16 v[82:85], v[216:219], v[220:223], v[82:85]
	ds_read_b128 v[220:223], v192 offset:8192
	s_waitcnt lgkmcnt(1)
	v_mfma_f32_16x16x32_bf16 v[78:81], v[204:207], v[198:201], v[78:81]
	v_mfma_f32_16x16x32_bf16 v[74:77], v[208:211], v[198:201], v[74:77]
	v_mfma_f32_16x16x32_bf16 v[70:73], v[212:215], v[198:201], v[70:73]
	v_mfma_f32_16x16x32_bf16 v[66:69], v[216:219], v[198:201], v[66:69]
	ds_read_b128 v[198:201], v192 offset:10240
	s_waitcnt lgkmcnt(1)
	v_mfma_f32_16x16x32_bf16 v[62:65], v[204:207], v[220:223], v[62:65]
	v_mfma_f32_16x16x32_bf16 v[58:61], v[208:211], v[220:223], v[58:61]
	v_mfma_f32_16x16x32_bf16 v[54:57], v[212:215], v[220:223], v[54:57]
	v_mfma_f32_16x16x32_bf16 v[50:53], v[216:219], v[220:223], v[50:53]
	ds_read_b128 v[220:223], v192 offset:12288
	s_waitcnt lgkmcnt(1)
	v_mfma_f32_16x16x32_bf16 v[46:49], v[204:207], v[198:201], v[46:49]
	v_mfma_f32_16x16x32_bf16 v[42:45], v[208:211], v[198:201], v[42:45]
	v_mfma_f32_16x16x32_bf16 v[38:41], v[212:215], v[198:201], v[38:41]
	v_mfma_f32_16x16x32_bf16 v[34:37], v[216:219], v[198:201], v[34:37]
	ds_read_b128 v[198:201], v192 offset:14336
	s_waitcnt lgkmcnt(1)
	v_mfma_f32_16x16x32_bf16 v[30:33], v[204:207], v[220:223], v[30:33]
	v_mfma_f32_16x16x32_bf16 v[26:29], v[208:211], v[220:223], v[26:29]
	v_mfma_f32_16x16x32_bf16 v[22:25], v[212:215], v[220:223], v[22:25]
	v_mfma_f32_16x16x32_bf16 v[18:21], v[216:219], v[220:223], v[18:21]
	s_waitcnt lgkmcnt(0)
	v_mfma_f32_16x16x32_bf16 v[14:17], v[204:207], v[198:201], v[14:17]
	v_mfma_f32_16x16x32_bf16 v[10:13], v[208:211], v[198:201], v[10:13]
	v_mfma_f32_16x16x32_bf16 v[6:9], v[212:215], v[198:201], v[6:9]
	v_mfma_f32_16x16x32_bf16 v[2:5], v[216:219], v[198:201], v[2:5]
	s_cmpk_eq_i32 s22, 0x780
	s_waitcnt vmcnt(0)
	s_barrier
	s_cbranch_scc0 .LBB0_107
	s_branch .LBB0_99

; #define MFMA16(a, b, c) __builtin_amdgcn_mfma_f32_16x16x32_bf16((a), (b), (c), 0, 0, 0)
;     ...
;   for (int kt = 0; kt < nk; ++kt) {
;     const int buf = kt & 1;
;     const char* cA = smem + buf * STAGE + (wm * 32 * MI + r16) * 128;
;     const char* cB = smem + buf * STAGE + 32768 + (wn * 64 + r16) * 128;
; #pragma unroll
;     for (int k2 = 0; k2 < 2; ++k2) {
;       if (k2 == 1 && kt + 1 < nk) STAGE_TILE(buf ^ 1, (kt + 1) * 64)
;       const int po = ((4 * k2 + q4) ^ swz) * 16;
;       bf16x8 bf[4];
; #pragma unroll
;       for (int nt = 0; nt < 4; ++nt) bf[nt] = *(const bf16x8*)(cB + nt * 16 * 128 + po);
;       bf16x8 afc = *(const bf16x8*)(cA + po);
; #pragma unroll
;       for (int a = 0; a < MT; ++a) {
;         bf16x8 afn = afc;
;         if (a + 1 < MT) afn = *(const bf16x8*)(cA + (a + 1) * 16 * 128 + po);
;         __builtin_amdgcn_sched_barrier(0);
; #pragma unroll
;         for (int nt = 0; nt < 4; ++nt) acc[a][nt] = MFMA16(bf[nt], afc, acc[a][nt]);
;         __builtin_amdgcn_sched_barrier(0);
;         afc = afn;
;       }
;     }
;     asm volatile("s_waitcnt vmcnt(0)" ::: "memory");
;     __syncthreads();
;   }
.LBB0_565:
	s_and_b32 s6, s5, 0x10000
	s_add_i32 s7, s6, 0
	v_add_u32_e32 v190, s7, v146
	v_add_u32_e32 v164, v190, v145
	v_add_u32_e32 v163, s7, v147
	ds_read_b128 v[148:151], v164 offset:32768
	ds_read_b128 v[152:155], v164 offset:34816
	ds_read_b128 v[156:159], v164 offset:36864
	ds_read_b128 v[164:167], v164 offset:38912
	v_add_u32_e32 v202, v163, v145
	ds_read_b128 v[168:171], v202
	ds_read_b128 v[172:175], v202 offset:2048
	s_xor_b32 s6, s6, 0x10000
	s_waitcnt lgkmcnt(1)
	v_mfma_f32_16x16x32_bf16 v[126:129], v[148:151], v[168:171], v[126:129]
	v_readfirstlane_b32 s7, v144
	v_mfma_f32_16x16x32_bf16 v[122:125], v[152:155], v[168:171], v[122:125]
	s_nop 0
	v_mfma_f32_16x16x32_bf16 v[118:121], v[156:159], v[168:171], v[118:121]
	s_add_u32 s7, s7, s6
	v_mfma_f32_16x16x32_bf16 v[114:117], v[164:167], v[168:171], v[114:117]
	ds_read_b128 v[168:171], v202 offset:4096
	s_add_u32 m0, s7, 0x0
	s_waitcnt lgkmcnt(1)
	v_mfma_f32_16x16x32_bf16 v[110:113], v[148:151], v[172:175], v[110:113]
	global_load_lds_dwordx4 v176, s[100:101]
	v_mfma_f32_16x16x32_bf16 v[106:109], v[152:155], v[172:175], v[106:109]
	s_add_u32 m0, s7, 0x2000
	v_mfma_f32_16x16x32_bf16 v[102:105], v[156:159], v[172:175], v[102:105]
	global_load_lds_dwordx4 v177, s[100:101]
	v_mfma_f32_16x16x32_bf16 v[98:101], v[164:167], v[172:175], v[98:101]
	ds_read_b128 v[172:175], v202 offset:6144
	s_add_u32 m0, s7, 0x4000
	s_waitcnt lgkmcnt(1)
	v_mfma_f32_16x16x32_bf16 v[94:97], v[148:151], v[168:171], v[94:97]
	global_load_lds_dwordx4 v178, s[100:101]
	v_mfma_f32_16x16x32_bf16 v[90:93], v[152:155], v[168:171], v[90:93]
	s_add_u32 m0, s7, 0x6000
	v_mfma_f32_16x16x32_bf16 v[86:89], v[156:159], v[168:171], v[86:89]
	global_load_lds_dwordx4 v179, s[100:101]
	v_mfma_f32_16x16x32_bf16 v[82:85], v[164:167], v[168:171], v[82:85]
	ds_read_b128 v[168:171], v202 offset:8192
	s_add_u32 m0, s7, 0x8000
	s_waitcnt lgkmcnt(1)
	v_mfma_f32_16x16x32_bf16 v[78:81], v[148:151], v[172:175], v[78:81]
	global_load_lds_dwordx4 v180, s[100:101]
	v_mfma_f32_16x16x32_bf16 v[74:77], v[152:155], v[172:175], v[74:77]
	s_add_u32 m0, s7, 0xa000
	v_mfma_f32_16x16x32_bf16 v[70:73], v[156:159], v[172:175], v[70:73]
	global_load_lds_dwordx4 v181, s[100:101]
	v_mfma_f32_16x16x32_bf16 v[66:69], v[164:167], v[172:175], v[66:69]
	ds_read_b128 v[172:175], v202 offset:10240
	s_add_u32 m0, s7, 0xc000
	s_waitcnt lgkmcnt(1)
	v_mfma_f32_16x16x32_bf16 v[62:65], v[148:151], v[168:171], v[62:65]
	global_load_lds_dwordx4 v182, s[100:101]
	v_mfma_f32_16x16x32_bf16 v[58:61], v[152:155], v[168:171], v[58:61]
	s_add_u32 m0, s7, 0xe000
	v_mfma_f32_16x16x32_bf16 v[54:57], v[156:159], v[168:171], v[54:57]
	global_load_lds_dwordx4 v183, s[100:101]
	v_mfma_f32_16x16x32_bf16 v[50:53], v[164:167], v[168:171], v[50:53]
	ds_read_b128 v[168:171], v202 offset:12288
	v_add_u32_e32 v203, v190, v143
	s_waitcnt lgkmcnt(1)
	v_mfma_f32_16x16x32_bf16 v[46:49], v[148:151], v[172:175], v[46:49]
	v_add_u32_e32 v192, v163, v143
	v_mfma_f32_16x16x32_bf16 v[42:45], v[152:155], v[172:175], v[42:45]
	ds_read_b128 v[204:207], v203 offset:32768
	v_mfma_f32_16x16x32_bf16 v[38:41], v[156:159], v[172:175], v[38:41]
	ds_read_b128 v[208:211], v203 offset:34816
	v_mfma_f32_16x16x32_bf16 v[34:37], v[164:167], v[172:175], v[34:37]
	ds_read_b128 v[172:175], v202 offset:14336
	ds_read_b128 v[212:215], v203 offset:36864
	s_waitcnt lgkmcnt(4)
	v_mfma_f32_16x16x32_bf16 v[30:33], v[148:151], v[168:171], v[30:33]
	ds_read_b128 v[216:219], v203 offset:38912
	v_mfma_f32_16x16x32_bf16 v[26:29], v[152:155], v[168:171], v[26:29]
	ds_read_b128 v[220:223], v192
	v_mfma_f32_16x16x32_bf16 v[22:25], v[156:159], v[168:171], v[22:25]
	ds_read_b128 v[198:201], v192 offset:2048
	v_mfma_f32_16x16x32_bf16 v[18:21], v[164:167], v[168:171], v[18:21]
	s_waitcnt lgkmcnt(4)
	v_mfma_f32_16x16x32_bf16 v[14:17], v[148:151], v[172:175], v[14:17]
	v_mfma_f32_16x16x32_bf16 v[10:13], v[152:155], v[172:175], v[10:13]
	v_mfma_f32_16x16x32_bf16 v[6:9], v[156:159], v[172:175], v[6:9]
	v_mfma_f32_16x16x32_bf16 v[2:5], v[164:167], v[172:175], v[2:5]
	s_waitcnt lgkmcnt(1)
	v_mfma_f32_16x16x32_bf16 v[126:129], v[204:207], v[220:223], v[126:129]
	s_add_u32 s100, s100, 0x80
	v_mfma_f32_16x16x32_bf16 v[122:125], v[208:211], v[220:223], v[122:125]
	s_addc_u32 s101, s101, 0
	v_mfma_f32_16x16x32_bf16 v[118:121], v[212:215], v[220:223], v[118:121]
	s_add_u32 s2, s2, 0x80
	v_mfma_f32_16x16x32_bf16 v[114:117], v[216:219], v[220:223], v[114:117]
	ds_read_b128 v[220:223], v192 offset:4096
	s_waitcnt lgkmcnt(1)
	v_mfma_f32_16x16x32_bf16 v[110:113], v[204:207], v[198:201], v[110:113]
	s_addc_u32 s3, s3, 0
	v_mfma_f32_16x16x32_bf16 v[106:109], v[208:211], v[198:201], v[106:109]
	s_add_i32 s5, s5, 0x10000
	v_mfma_f32_16x16x32_bf16 v[102:105], v[212:215], v[198:201], v[102:105]
	v_mfma_f32_16x16x32_bf16 v[98:101], v[216:219], v[198:201], v[98:101]
	ds_read_b128 v[198:201], v192 offset:6144
	s_waitcnt lgkmcnt(1)
	v_mfma_f32_16x16x32_bf16 v[94:97], v[204:207], v[220:223], v[94:97]
	v_mfma_f32_16x16x32_bf16 v[90:93], v[208:211], v[220:223], v[90:93]
	v_mfma_f32_16x16x32_bf16 v[86:89], v[212:215], v[220:223], v[86:89]
	v_mfma_f32_16x16x32_bf16 v[82:85], v[216:219], v[220:223], v[82:85]
	ds_read_b128 v[220:223], v192 offset:8192
	s_waitcnt lgkmcnt(1)
	v_mfma_f32_16x16x32_bf16 v[78:81], v[204:207], v[198:201], v[78:81]
	v_mfma_f32_16x16x32_bf16 v[74:77], v[208:211], v[198:201], v[74:77]
	v_mfma_f32_16x16x32_bf16 v[70:73], v[212:215], v[198:201], v[70:73]
	v_mfma_f32_16x16x32_bf16 v[66:69], v[216:219], v[198:201], v[66:69]
	ds_read_b128 v[198:201], v192 offset:10240
	s_waitcnt lgkmcnt(1)
	v_mfma_f32_16x16x32_bf16 v[62:65], v[204:207], v[220:223], v[62:65]
	v_mfma_f32_16x16x32_bf16 v[58:61], v[208:211], v[220:223], v[58:61]
	v_mfma_f32_16x16x32_bf16 v[54:57], v[212:215], v[220:223], v[54:57]
	v_mfma_f32_16x16x32_bf16 v[50:53], v[216:219], v[220:223], v[50:53]
	ds_read_b128 v[220:223], v192 offset:12288
	s_waitcnt lgkmcnt(1)
	v_mfma_f32_16x16x32_bf16 v[46:49], v[204:207], v[198:201], v[46:49]
	v_mfma_f32_16x16x32_bf16 v[42:45], v[208:211], v[198:201], v[42:45]
	v_mfma_f32_16x16x32_bf16 v[38:41], v[212:215], v[198:201], v[38:41]
	v_mfma_f32_16x16x32_bf16 v[34:37], v[216:219], v[198:201], v[34:37]
	ds_read_b128 v[198:201], v192 offset:14336
	s_waitcnt lgkmcnt(1)
	v_mfma_f32_16x16x32_bf16 v[30:33], v[204:207], v[220:223], v[30:33]
	v_mfma_f32_16x16x32_bf16 v[26:29], v[208:211], v[220:223], v[26:29]
	v_mfma_f32_16x16x32_bf16 v[22:25], v[212:215], v[220:223], v[22:25]
	v_mfma_f32_16x16x32_bf16 v[18:21], v[216:219], v[220:223], v[18:21]
	s_waitcnt lgkmcnt(0)
	v_mfma_f32_16x16x32_bf16 v[14:17], v[204:207], v[198:201], v[14:17]
	v_mfma_f32_16x16x32_bf16 v[10:13], v[208:211], v[198:201], v[10:13]
	v_mfma_f32_16x16x32_bf16 v[6:9], v[212:215], v[198:201], v[6:9]
	v_mfma_f32_16x16x32_bf16 v[2:5], v[216:219], v[198:201], v[2:5]
	s_cmpk_eq_i32 s2, 0x780
	s_waitcnt vmcnt(0)
	s_barrier
; #define MFMA16(a, b, c) __builtin_amdgcn_mfma_f32_16x16x32_bf16((a), (b), (c), 0, 0, 0)
;     ...
;   for (int kt = 0; kt < nk; ++kt) {
;     const int buf = kt & 1;
;     const char* cA = smem + buf * STAGE + (wm * 32 * MI + r16) * 128;
;     const char* cB = smem + buf * STAGE + 32768 + (wn * 64 + r16) * 128;
; #pragma unroll
;     for (int k2 = 0; k2 < 2; ++k2) {
;       if (k2 == 1 && kt + 1 < nk) STAGE_TILE(buf ^ 1, (kt + 1) * 64)
;       const int po = ((4 * k2 + q4) ^ swz) * 16;
;       bf16x8 bf[4];
; #pragma unroll
;       for (int nt = 0; nt < 4; ++nt) bf[nt] = *(const bf16x8*)(cB + nt * 16 * 128 + po);
;       bf16x8 afc = *(const bf16x8*)(cA + po);
; #pragma unroll
;       for (int a = 0; a < MT; ++a) {
;         bf16x8 afn = afc;
;         if (a + 1 < MT) afn = *(const bf16x8*)(cA + (a + 1) * 16 * 128 + po);
;         __builtin_amdgcn_sched_barrier(0);
; #pragma unroll
;         for (int nt = 0; nt < 4; ++nt) acc[a][nt] = MFMA16(bf[nt], afc, acc[a][nt]);
;         __builtin_amdgcn_sched_barrier(0);
;         afc = afn;
;       }
;     }
;     asm volatile("s_waitcnt vmcnt(0)" ::: "memory");
;     __syncthreads();
;   }
;     ...
;   const int row0 = m0 + wm * 32 * MI + r16, cbw = n0 + wn * 64;
	s_cbranch_scc0 .LBB0_565
	s_add_i32 s2, 0, 0x10000
	v_add_u32_e32 v138, s2, v147
	v_readlane_b32 s2, v254, 18
	s_nop 1
	v_add_u32_e32 v139, s2, v146
	v_add_u32_e32 v144, v139, v145
	ds_read_b128 v[130:133], v144
	ds_read_b128 v[134:137], v144 offset:2048
	ds_read_b128 v[146:149], v144 offset:4096
	ds_read_b128 v[150:153], v144 offset:6144
	v_add_u32_e32 v144, v138, v145
	ds_read_b128 v[154:157], v144
	ds_read_b128 v[158:161], v144 offset:2048
	s_waitcnt lgkmcnt(1)
	v_mfma_f32_16x16x32_bf16 v[122:125], v[134:137], v[154:157], v[122:125]
	v_mfma_f32_16x16x32_bf16 v[118:121], v[146:149], v[154:157], v[118:121]
	v_mfma_f32_16x16x32_bf16 v[114:117], v[150:153], v[154:157], v[114:117]
	v_mfma_f32_16x16x32_bf16 v[126:129], v[130:133], v[154:157], v[126:129]
	ds_read_b128 v[154:157], v144 offset:4096
	s_waitcnt lgkmcnt(1)
	v_mfma_f32_16x16x32_bf16 v[110:113], v[130:133], v[158:161], v[110:113]
	v_mfma_f32_16x16x32_bf16 v[106:109], v[134:137], v[158:161], v[106:109]
	v_mfma_f32_16x16x32_bf16 v[102:105], v[146:149], v[158:161], v[102:105]
	v_mfma_f32_16x16x32_bf16 v[98:101], v[150:153], v[158:161], v[98:101]
	ds_read_b128 v[158:161], v144 offset:6144
	s_waitcnt lgkmcnt(1)
	v_mfma_f32_16x16x32_bf16 v[94:97], v[130:133], v[154:157], v[94:97]
	v_mfma_f32_16x16x32_bf16 v[90:93], v[134:137], v[154:157], v[90:93]
	v_mfma_f32_16x16x32_bf16 v[86:89], v[146:149], v[154:157], v[86:89]
	v_mfma_f32_16x16x32_bf16 v[82:85], v[150:153], v[154:157], v[82:85]
	ds_read_b128 v[154:157], v144 offset:8192
	s_waitcnt lgkmcnt(1)
	v_mfma_f32_16x16x32_bf16 v[78:81], v[130:133], v[158:161], v[78:81]
	v_mfma_f32_16x16x32_bf16 v[74:77], v[134:137], v[158:161], v[74:77]
	v_mfma_f32_16x16x32_bf16 v[70:73], v[146:149], v[158:161], v[70:73]
	v_mfma_f32_16x16x32_bf16 v[66:69], v[150:153], v[158:161], v[66:69]
	ds_read_b128 v[158:161], v144 offset:10240
	s_waitcnt lgkmcnt(1)
	v_mfma_f32_16x16x32_bf16 v[62:65], v[130:133], v[154:157], v[62:65]
	v_mfma_f32_16x16x32_bf16 v[58:61], v[134:137], v[154:157], v[58:61]
	v_mfma_f32_16x16x32_bf16 v[54:57], v[146:149], v[154:157], v[54:57]
	v_mfma_f32_16x16x32_bf16 v[50:53], v[150:153], v[154:157], v[50:53]
	ds_read_b128 v[154:157], v144 offset:12288
	s_waitcnt lgkmcnt(1)
	v_mfma_f32_16x16x32_bf16 v[46:49], v[130:133], v[158:161], v[46:49]
	v_mfma_f32_16x16x32_bf16 v[42:45], v[134:137], v[158:161], v[42:45]
	v_mfma_f32_16x16x32_bf16 v[38:41], v[146:149], v[158:161], v[38:41]
	v_mfma_f32_16x16x32_bf16 v[34:37], v[150:153], v[158:161], v[34:37]
	ds_read_b128 v[158:161], v144 offset:14336
	s_waitcnt lgkmcnt(1)
	v_mfma_f32_16x16x32_bf16 v[30:33], v[130:133], v[154:157], v[30:33]
	v_mfma_f32_16x16x32_bf16 v[26:29], v[134:137], v[154:157], v[26:29]
	v_mfma_f32_16x16x32_bf16 v[22:25], v[146:149], v[154:157], v[22:25]
	v_mfma_f32_16x16x32_bf16 v[18:21], v[150:153], v[154:157], v[18:21]
	s_waitcnt lgkmcnt(0)
	v_mfma_f32_16x16x32_bf16 v[14:17], v[130:133], v[158:161], v[14:17]
	v_mfma_f32_16x16x32_bf16 v[10:13], v[134:137], v[158:161], v[10:13]
	v_mfma_f32_16x16x32_bf16 v[6:9], v[146:149], v[158:161], v[6:9]
	v_mfma_f32_16x16x32_bf16 v[2:5], v[150:153], v[158:161], v[2:5]
	v_add_u32_e32 v130, v139, v143
	ds_read_b128 v[134:137], v130
	ds_read_b128 v[144:147], v130 offset:2048
	ds_read_b128 v[148:151], v130 offset:4096
	ds_read_b128 v[152:155], v130 offset:6144
	v_add_u32_e32 v138, v138, v143
	ds_read_b128 v[156:159], v138
	ds_read_b128 v[164:167], v138 offset:2048
	s_waitcnt lgkmcnt(1)
	v_mfma_f32_16x16x32_bf16 v[130:133], v[134:137], v[156:159], v[126:129]
	v_mfma_f32_16x16x32_bf16 v[122:125], v[144:147], v[156:159], v[122:125]
	v_mfma_f32_16x16x32_bf16 v[118:121], v[148:151], v[156:159], v[118:121]
	v_mfma_f32_16x16x32_bf16 v[114:117], v[152:155], v[156:159], v[114:117]
	ds_read_b128 v[126:129], v138 offset:4096
	s_waitcnt lgkmcnt(1)
	v_mfma_f32_16x16x32_bf16 v[110:113], v[134:137], v[164:167], v[110:113]
	v_mfma_f32_16x16x32_bf16 v[106:109], v[144:147], v[164:167], v[106:109]
	v_mfma_f32_16x16x32_bf16 v[102:105], v[148:151], v[164:167], v[102:105]
	v_mfma_f32_16x16x32_bf16 v[98:101], v[152:155], v[164:167], v[98:101]
	ds_read_b128 v[156:159], v138 offset:6144
	s_waitcnt lgkmcnt(1)
	v_mfma_f32_16x16x32_bf16 v[94:97], v[134:137], v[126:129], v[94:97]
	v_mfma_f32_16x16x32_bf16 v[90:93], v[144:147], v[126:129], v[90:93]
	v_mfma_f32_16x16x32_bf16 v[86:89], v[148:151], v[126:129], v[86:89]
	v_mfma_f32_16x16x32_bf16 v[82:85], v[152:155], v[126:129], v[82:85]
	ds_read_b128 v[126:129], v138 offset:8192
	s_waitcnt lgkmcnt(1)
	v_mfma_f32_16x16x32_bf16 v[78:81], v[134:137], v[156:159], v[78:81]
	v_mfma_f32_16x16x32_bf16 v[74:77], v[144:147], v[156:159], v[74:77]
	v_mfma_f32_16x16x32_bf16 v[70:73], v[148:151], v[156:159], v[70:73]
	v_mfma_f32_16x16x32_bf16 v[66:69], v[152:155], v[156:159], v[66:69]
	ds_read_b128 v[156:159], v138 offset:10240
	s_waitcnt lgkmcnt(1)
	v_mfma_f32_16x16x32_bf16 v[62:65], v[134:137], v[126:129], v[62:65]
	v_mfma_f32_16x16x32_bf16 v[58:61], v[144:147], v[126:129], v[58:61]
	v_mfma_f32_16x16x32_bf16 v[54:57], v[148:151], v[126:129], v[54:57]
	v_mfma_f32_16x16x32_bf16 v[50:53], v[152:155], v[126:129], v[50:53]
	ds_read_b128 v[126:129], v138 offset:12288
	s_waitcnt lgkmcnt(1)
	v_mfma_f32_16x16x32_bf16 v[46:49], v[134:137], v[156:159], v[46:49]
	v_mfma_f32_16x16x32_bf16 v[42:45], v[144:147], v[156:159], v[42:45]
	v_mfma_f32_16x16x32_bf16 v[38:41], v[148:151], v[156:159], v[38:41]
	v_mfma_f32_16x16x32_bf16 v[34:37], v[152:155], v[156:159], v[34:37]
	ds_read_b128 v[156:159], v138 offset:14336
	s_waitcnt lgkmcnt(1)
	v_mfma_f32_16x16x32_bf16 v[30:33], v[134:137], v[126:129], v[30:33]
	v_mfma_f32_16x16x32_bf16 v[26:29], v[144:147], v[126:129], v[26:29]
	v_mfma_f32_16x16x32_bf16 v[22:25], v[148:151], v[126:129], v[22:25]
	v_mfma_f32_16x16x32_bf16 v[18:21], v[152:155], v[126:129], v[18:21]
	s_waitcnt lgkmcnt(0)
	v_mfma_f32_16x16x32_bf16 v[14:17], v[134:137], v[156:159], v[14:17]
	v_mfma_f32_16x16x32_bf16 v[10:13], v[144:147], v[156:159], v[10:13]
	v_mfma_f32_16x16x32_bf16 v[6:9], v[148:151], v[156:159], v[6:9]
	v_mfma_f32_16x16x32_bf16 v[2:5], v[152:155], v[156:159], v[2:5]
	s_waitcnt vmcnt(0)
	v_lshl_or_b32 v190, v142, 6, s22
	s_movk_i32 s2, 0x981
	v_cmp_gt_i32_e32 vcc, s2, v190
	s_barrier
; DI bf16_t f2bf(float x) { return (bf16_t)(pack2(x, 0.f) & 0xffffu); }
; DI void phase_win(char* smem, const Params& p, int layer) {
;     ...
;   auto ep = [&](int row, int cbw, int q4, const f32x4& c0, const f32x4& c1, const f32x4& c2, const f32x4& c3) {
;     if (cbw > 2432) return;
;     const int b = row / TT, t = row - b * TT;
;     const bool lat = t >= CTXL;
;     const int pos = t - CTXL;
;     float v[16] = {c0[0], c0[1], c0[2], c0[3], c1[0], c1[1], c1[2], c1[3], c2[0], c2[1], c2[2], c2[3], c3[0], c3[1], c3[2], c3[3]};
;     if (cbw >= 640 && cbw < 768) {
;       bf16_t* vp = p.VsT + ((size_t)(b * 2 + ((cbw - 640) >> 6)) * 64 + q4 * 16) * TT + t;
; #pragma unroll
;       for (int i = 0; i < 16; ++i) vp[(size_t)i * TT] = f2bf(v[i]);
;       return;
;     }
;     const bool r16 = cbw >= 256 && cbw < 640, rkr = cbw == 2432;
;     if (rkr && q4 >= 2) return;
;     if (lat && (r16 || rkr)) {
;       const int a = r16 ? (q4 >> 1) : q4;
;       const int pa = a ? (pos & 63) : (pos >> 6);
;       const float* tab = r16 ? p.ropeS + 2 * (pa * 16 + (q4 & 1) * 8) : p.ropeM + 2 * (pa * 8);
; #pragma unroll
;       for (int k = 0; k < 4; ++k) {
;         const float4 cs = *(const float4*)(tab + 4 * k);
;         const float x0 = v[4 * k], x1 = v[4 * k + 1], x2 = v[4 * k + 2], x3 = v[4 * k + 3];
;         v[4 * k] = x0 * cs.x - x1 * cs.y; v[4 * k + 1] = x1 * cs.x + x0 * cs.y;
;         v[4 * k + 2] = x2 * cs.z - x3 * cs.w; v[4 * k + 3] = x3 * cs.z + x2 * cs.w;
;       }
;     }
	s_and_saveexec_b64 s[96:97], vcc
	s_cbranch_execz .LBB0_557
	v_or_b32_e32 v126, s4, v162
	v_lshl_add_u32 v136, v141, 7, v126
	v_and_b32_e32 v126, 0xffffff80, v190
	s_movk_i32 s2, 0x280
	v_cmp_ne_u32_e64 s[16:17], s2, v126
	s_movk_i32 s2, 0x27f
	v_cmp_lt_i32_e64 s[4:5], s2, v190
	s_movk_i32 s2, 0x980
	v_cmp_ne_u32_e64 s[8:9], s2, v190
	v_cmp_gt_u32_e64 s[6:7], 2, v140
	v_add_u32_e32 v126, 0xffffff00, v190
	v_cmp_eq_u32_e32 vcc, s2, v190
	s_or_b64 s[2:3], s[8:9], s[6:7]
	s_movk_i32 s6, 0x180
	v_cmp_gt_u32_e64 s[12:13], s6, v126
	s_or_b64 s[86:87], vcc, s[12:13]
	v_lshrrev_b32_e32 v160, 6, v126
	v_cndmask_b32_e64 v127, 0, 1, s[12:13]
	v_lshrrev_b32_e32 v127, v127, v140
	v_cmp_eq_u32_e64 s[14:15], 0, v127
	v_add_u32_e32 v127, 0xfffffe00, v190
	v_mul_hi_i32 v126, v136, s1
	s_cmp_eq_u32 s10, 1
	v_lshrrev_b32_e32 v159, 6, v127
	v_lshrrev_b32_e32 v127, 31, v126
	v_ashrrev_i32_e32 v126, 11, v126
	v_lshlrev_b32_e32 v158, 4, v140
	s_movk_i32 s6, 0x1ff
	s_cselect_b64 s[94:95], -1, 0
	s_movk_i32 s10, 0xff
	s_cmpk_gt_u32 s22, 0x7ff
	v_add_u32_e32 v139, v126, v127
	v_and_b32_e32 v161, 16, v158
	v_cmp_lt_i32_e64 s[6:7], s6, v190
	v_cmp_lt_i32_e64 s[10:11], s10, v190
	s_cselect_b64 s[22:23], -1, 0
	v_ashrrev_i32_e32 v135, 31, v190
	v_mov_b32_e32 v134, v190
	v_mad_i32_i24 v138, v139, s80, v136
	s_and_saveexec_b64 s[30:31], s[16:17]
	s_xor_b64 s[30:31], exec, s[30:31]
	s_cbranch_execz .LBB0_594
	s_and_saveexec_b64 s[52:53], s[2:3]
	s_cbranch_execz .LBB0_593
	s_movk_i32 s45, 0xff
	v_cmp_lt_i32_e32 vcc, s45, v138
	s_and_b64 s[46:47], s[86:87], vcc
	v_mov_b32_e32 v140, v131
	v_mov_b32_e32 v141, v133
	v_mov_b32_e32 v142, v123
	v_mov_b32_e32 v143, v125
	v_mov_b32_e32 v144, v119
	v_mov_b32_e32 v145, v121
	v_mov_b32_e32 v154, v115
	v_mov_b32_e32 v155, v117
	v_mov_b32_e32 v146, v130
	v_mov_b32_e32 v147, v132
	v_mov_b32_e32 v148, v122
	v_mov_b32_e32 v149, v124
	v_mov_b32_e32 v150, v118
	v_mov_b32_e32 v151, v120
	v_mov_b32_e32 v152, v114
	v_mov_b32_e32 v153, v116
	s_and_saveexec_b64 s[54:55], s[46:47]
	s_cbranch_execz .LBB0_571
	v_readlane_b32 s46, v252, 1
	v_cndmask_b32_e64 v128, v238, v240, s[12:13]
	v_mov_b32_e32 v129, v191
	v_readlane_b32 s47, v252, 2
	v_add_u32_e32 v126, 0xffffff00, v138
	v_lshrrev_b32_e32 v126, 6, v126
	v_lshl_add_u64 v[128:129], s[46:47], 0, v[128:129]
	global_load_dwordx2 v[128:129], v[128:129], off
	v_cndmask_b32_e64 v126, v162, v126, s[14:15]
	v_lshlrev_b32_e32 v127, 4, v126
	v_lshl_or_b32 v126, v126, 5, v161
	v_cndmask_b32_e64 v126, v127, v126, s[12:13]
	v_mov_b32_e32 v127, v191
	v_mov_b32_e32 v182, v130
	v_mov_b32_e32 v183, v133
	v_mov_b32_e32 v130, v131
	v_mov_b32_e32 v131, v132
	s_waitcnt vmcnt(0)
	v_lshl_add_u64 v[156:157], v[126:127], 2, v[128:129]
	global_load_dwordx4 v[126:129], v[156:157], off offset:48
	global_load_dwordx4 v[164:167], v[156:157], off offset:32
	global_load_dwordx4 v[168:171], v[156:157], off offset:16
	global_load_dwordx4 v[172:175], v[156:157], off
	s_waitcnt vmcnt(3)
	v_mov_b32_e32 v156, v127
	s_waitcnt vmcnt(2)
	v_mov_b32_e32 v180, v165
	s_waitcnt vmcnt(1)
	v_mov_b32_e32 v178, v169
	s_waitcnt vmcnt(0)
	v_mov_b32_e32 v132, v172
	v_mov_b32_e32 v133, v175
	v_mov_b32_e32 v176, v173
	v_mov_b32_e32 v177, v174
	v_pk_mul_f32 v[130:131], v[130:131], v[132:133]
	v_mov_b32_e32 v132, v173
	v_pk_mul_f32 v[132:133], v[140:141], v[132:133]
	v_pk_fma_f32 v[140:141], v[182:183], v[176:177], v[130:131]
	v_mov_b32_e32 v130, v122
	v_mov_b32_e32 v131, v125
	v_mov_b32_e32 v122, v123
	v_mov_b32_e32 v123, v124
	v_mov_b32_e32 v124, v168
	v_mov_b32_e32 v125, v171
	v_mov_b32_e32 v179, v170
	v_pk_mul_f32 v[122:123], v[122:123], v[124:125]
	v_mov_b32_e32 v124, v169
	v_pk_mul_f32 v[124:125], v[142:143], v[124:125]
	v_pk_fma_f32 v[142:143], v[130:131], v[178:179], v[122:123]
	v_mov_b32_e32 v122, v118
	v_mov_b32_e32 v123, v121
	v_mov_b32_e32 v118, v119
	v_mov_b32_e32 v119, v120
	v_mov_b32_e32 v120, v164
	v_mov_b32_e32 v121, v167
	v_mov_b32_e32 v181, v166
	v_pk_mul_f32 v[118:119], v[118:119], v[120:121]
	v_mov_b32_e32 v120, v165
	v_pk_mul_f32 v[120:121], v[144:145], v[120:121]
	v_pk_fma_f32 v[144:145], v[122:123], v[180:181], v[118:119]
	v_mov_b32_e32 v118, v114
	v_mov_b32_e32 v119, v117
	v_mov_b32_e32 v114, v115
	v_mov_b32_e32 v115, v116
	v_mov_b32_e32 v116, v126
	v_mov_b32_e32 v117, v129
	v_pk_mul_f32 v[114:115], v[114:115], v[116:117]
	v_mov_b32_e32 v116, v127
	v_mov_b32_e32 v157, v128
	v_mov_b32_e32 v173, v174
	v_mov_b32_e32 v169, v170
	v_mov_b32_e32 v165, v166
	v_pk_mul_f32 v[116:117], v[154:155], v[116:117]
	v_mov_b32_e32 v127, v128
	v_pk_fma_f32 v[146:147], v[146:147], v[172:173], v[132:133] neg_lo:[0,0,1] neg_hi:[0,0,1]
	v_pk_fma_f32 v[148:149], v[148:149], v[168:169], v[124:125] neg_lo:[0,0,1] neg_hi:[0,0,1]
	v_pk_fma_f32 v[150:151], v[150:151], v[164:165], v[120:121] neg_lo:[0,0,1] neg_hi:[0,0,1]
	v_pk_fma_f32 v[152:153], v[152:153], v[126:127], v[116:117] neg_lo:[0,0,1] neg_hi:[0,0,1]
	v_pk_fma_f32 v[154:155], v[118:119], v[156:157], v[114:115]
